# scan waves: the two packed state+v*kd FMAs split into four scalar FMAs that fill the DPP wait-state gaps (no s_nop pads left in the steady-state step)
# baseline (speedup 1.0000x reference)
.Lsc_S_go:
	ds_read_b128 v[144:147], v34 offset:32768
	ds_read_b128 v[156:159], v35 offset:0
	ds_read_b128 v[76:79], v34 offset:0
	ds_read_b128 v[80:83], v34 offset:256
	ds_read_b128 v[84:87], v34 offset:512
	ds_read_b128 v[88:91], v34 offset:768
	ds_read_b128 v[92:95], v34 offset:1024
	ds_read_b128 v[96:99], v34 offset:1280
	ds_read_b128 v[100:103], v34 offset:1536
	ds_read_b128 v[104:107], v34 offset:1792
	s_waitcnt lgkmcnt(9)
	v_pk_mul_f32 v[24:25], v[10:11], v[144:145]
	v_pk_fma_f32 v[24:25], v[8:9], v[146:147], v[24:25]
	v_add_f32_e32 v24, v24, v25
	s_waitcnt lgkmcnt(7)
	v_fma_f32 v16, v76, v156, v10
	v_fma_f32 v17, v77, v156, v11
	v_add_f32_dpp v15, v24, v24 row_ror:8 row_mask:0xf bank_mask:0xf bound_ctrl:1
	v_fma_f32 v18, v78, v156, v8
	v_fma_f32 v19, v79, v156, v9
	v_add_f32_dpp v15, v15, v15 row_ror:4 row_mask:0xf bank_mask:0xf bound_ctrl:1
	ds_read_b128 v[108:111], v34 offset:2048
	ds_read_b128 v[112:115], v34 offset:2304
	v_add_f32_dpp v15, v15, v15 row_ror:2 row_mask:0xf bank_mask:0xf bound_ctrl:1
	ds_read_b128 v[116:119], v34 offset:2560
	ds_read_b128 v[120:123], v34 offset:2816
	v_add_f32_dpp v30, v15, v15 row_ror:1 row_mask:0xf bank_mask:0xf bound_ctrl:1
	s_waitcnt lgkmcnt(0)
.Lsc_S_loop:
	s_waitcnt lgkmcnt(3)
	v_pk_fma_f32 v[10:11], v[80:81], v[30:31], v[16:17] op_sel_hi:[1,0,1] neg_lo:[0,1,0] neg_hi:[0,1,0]
	v_pk_fma_f32 v[8:9], v[82:83], v[30:31], v[18:19] op_sel_hi:[1,0,1] neg_lo:[0,1,0] neg_hi:[0,1,0]
	v_pk_mul_f32 v[24:25], v[10:11], v[84:85] op_sel:[0,0] op_sel_hi:[0,1]
	v_pk_fma_f32 v[24:25], v[10:11], v[86:87], v[24:25] op_sel:[1,0,0] op_sel_hi:[1,1,1]
	v_pk_fma_f32 v[24:25], v[8:9], v[88:89], v[24:25] op_sel:[0,0,0] op_sel_hi:[0,1,1]
	v_pk_fma_f32 v[24:25], v[8:9], v[90:91], v[24:25] op_sel:[1,0,0] op_sel_hi:[1,1,1]
	v_fma_f32 v16, v92, v157, v10
	v_fma_f32 v17, v93, v157, v11
	v_add_f32_dpp v15, v24, v24 row_ror:8 row_mask:0xf bank_mask:0xf bound_ctrl:1
	v_fma_f32 v18, v94, v157, v8
	ds_read_b128 v[124:127], v34 offset:3072
	v_add_f32_dpp v15, v15, v15 row_ror:4 row_mask:0xf bank_mask:0xf bound_ctrl:1
	ds_read_b128 v[128:131], v34 offset:3328
	ds_read_b128 v[132:135], v34 offset:3584
	v_add_f32_dpp v15, v15, v15 row_ror:2 row_mask:0xf bank_mask:0xf bound_ctrl:1
	v_fma_f32 v19, v95, v157, v9
	ds_read_b128 v[136:139], v34 offset:3840
	ds_read_b128 v[160:163], v35 offset:16
	v_add_f32_dpp v30, v15, v15 row_ror:1 row_mask:0xf bank_mask:0xf bound_ctrl:1
	v_pk_fma_f32 v[10:11], v[96:97], v[30:31], v[16:17] op_sel_hi:[1,0,1] neg_lo:[0,1,0] neg_hi:[0,1,0]
	v_pk_fma_f32 v[8:9], v[98:99], v[30:31], v[18:19] op_sel_hi:[1,0,1] neg_lo:[0,1,0] neg_hi:[0,1,0]
	v_pk_mul_f32 v[26:27], v[10:11], v[100:101] op_sel:[0,0] op_sel_hi:[0,1]
	v_pk_fma_f32 v[26:27], v[10:11], v[102:103], v[26:27] op_sel:[1,0,0] op_sel_hi:[1,1,1]
	v_pk_fma_f32 v[26:27], v[8:9], v[104:105], v[26:27] op_sel:[0,0,0] op_sel_hi:[0,1,1]
	v_pk_fma_f32 v[26:27], v[8:9], v[106:107], v[26:27] op_sel:[1,0,0] op_sel_hi:[1,1,1]
	v_fma_f32 v16, v108, v158, v10
	v_fma_f32 v17, v109, v158, v11
	v_add_f32_dpp v15, v26, v26 row_ror:8 row_mask:0xf bank_mask:0xf bound_ctrl:1
	v_fma_f32 v18, v110, v158, v8
	ds_read_b128 v[76:79], v34 offset:4096
	v_add_f32_dpp v15, v15, v15 row_ror:4 row_mask:0xf bank_mask:0xf bound_ctrl:1
	ds_read_b128 v[80:83], v34 offset:4352
	ds_read_b128 v[84:87], v34 offset:4608
	v_add_f32_dpp v15, v15, v15 row_ror:2 row_mask:0xf bank_mask:0xf bound_ctrl:1
	v_fma_f32 v19, v111, v158, v9
	ds_read_b128 v[88:91], v34 offset:4864
	ds_write2st64_b32 v37, v25, v27 offset0:0 offset1:4
	v_add_f32_dpp v30, v15, v15 row_ror:1 row_mask:0xf bank_mask:0xf bound_ctrl:1
	s_waitcnt lgkmcnt(4)
	v_pk_fma_f32 v[10:11], v[112:113], v[30:31], v[16:17] op_sel_hi:[1,0,1] neg_lo:[0,1,0] neg_hi:[0,1,0]
	v_pk_fma_f32 v[8:9], v[114:115], v[30:31], v[18:19] op_sel_hi:[1,0,1] neg_lo:[0,1,0] neg_hi:[0,1,0]
	v_pk_mul_f32 v[24:25], v[10:11], v[116:117] op_sel:[0,0] op_sel_hi:[0,1]
	v_pk_fma_f32 v[24:25], v[10:11], v[118:119], v[24:25] op_sel:[1,0,0] op_sel_hi:[1,1,1]
	v_pk_fma_f32 v[24:25], v[8:9], v[120:121], v[24:25] op_sel:[0,0,0] op_sel_hi:[0,1,1]
	v_pk_fma_f32 v[24:25], v[8:9], v[122:123], v[24:25] op_sel:[1,0,0] op_sel_hi:[1,1,1]
	v_fma_f32 v16, v124, v159, v10
	v_fma_f32 v17, v125, v159, v11
	v_add_f32_dpp v15, v24, v24 row_ror:8 row_mask:0xf bank_mask:0xf bound_ctrl:1
	v_fma_f32 v18, v126, v159, v8
	ds_read_b128 v[92:95], v34 offset:5120
	v_add_f32_dpp v15, v15, v15 row_ror:4 row_mask:0xf bank_mask:0xf bound_ctrl:1
	ds_read_b128 v[96:99], v34 offset:5376
	ds_read_b128 v[100:103], v34 offset:5632
	v_add_f32_dpp v15, v15, v15 row_ror:2 row_mask:0xf bank_mask:0xf bound_ctrl:1
	v_fma_f32 v19, v127, v159, v9
	ds_read_b128 v[104:107], v34 offset:5888
	v_add_f32_dpp v30, v15, v15 row_ror:1 row_mask:0xf bank_mask:0xf bound_ctrl:1
	v_pk_fma_f32 v[10:11], v[128:129], v[30:31], v[16:17] op_sel_hi:[1,0,1] neg_lo:[0,1,0] neg_hi:[0,1,0]
	v_pk_fma_f32 v[8:9], v[130:131], v[30:31], v[18:19] op_sel_hi:[1,0,1] neg_lo:[0,1,0] neg_hi:[0,1,0]
	v_pk_mul_f32 v[26:27], v[10:11], v[132:133] op_sel:[0,0] op_sel_hi:[0,1]
	v_pk_fma_f32 v[26:27], v[10:11], v[134:135], v[26:27] op_sel:[1,0,0] op_sel_hi:[1,1,1]
	v_pk_fma_f32 v[26:27], v[8:9], v[136:137], v[26:27] op_sel:[0,0,0] op_sel_hi:[0,1,1]
	v_pk_fma_f32 v[26:27], v[8:9], v[138:139], v[26:27] op_sel:[1,0,0] op_sel_hi:[1,1,1]
	v_fma_f32 v16, v76, v160, v10
	v_fma_f32 v17, v77, v160, v11
	v_add_f32_dpp v15, v26, v26 row_ror:8 row_mask:0xf bank_mask:0xf bound_ctrl:1
	v_fma_f32 v18, v78, v160, v8
	ds_read_b128 v[108:111], v34 offset:6144
	v_add_f32_dpp v15, v15, v15 row_ror:4 row_mask:0xf bank_mask:0xf bound_ctrl:1
	ds_read_b128 v[112:115], v34 offset:6400
	ds_read_b128 v[116:119], v34 offset:6656
	v_add_f32_dpp v15, v15, v15 row_ror:2 row_mask:0xf bank_mask:0xf bound_ctrl:1
	v_fma_f32 v19, v79, v160, v9
	ds_read_b128 v[120:123], v34 offset:6912
	ds_read_b128 v[140:143], v34 offset:33792
	ds_write2st64_b32 v37, v25, v27 offset0:8 offset1:12
	v_add_f32_dpp v30, v15, v15 row_ror:1 row_mask:0xf bank_mask:0xf bound_ctrl:1
	s_waitcnt lgkmcnt(5)
	v_pk_fma_f32 v[10:11], v[80:81], v[30:31], v[16:17] op_sel_hi:[1,0,1] neg_lo:[0,1,0] neg_hi:[0,1,0]
	v_pk_fma_f32 v[8:9], v[82:83], v[30:31], v[18:19] op_sel_hi:[1,0,1] neg_lo:[0,1,0] neg_hi:[0,1,0]
	v_pk_mul_f32 v[24:25], v[10:11], v[84:85] op_sel:[0,0] op_sel_hi:[0,1]
	v_pk_fma_f32 v[24:25], v[10:11], v[86:87], v[24:25] op_sel:[1,0,0] op_sel_hi:[1,1,1]
	v_pk_fma_f32 v[24:25], v[8:9], v[88:89], v[24:25] op_sel:[0,0,0] op_sel_hi:[0,1,1]
	v_pk_fma_f32 v[24:25], v[8:9], v[90:91], v[24:25] op_sel:[1,0,0] op_sel_hi:[1,1,1]
	v_fma_f32 v16, v92, v161, v10
	v_fma_f32 v17, v93, v161, v11
	v_add_f32_dpp v15, v24, v24 row_ror:8 row_mask:0xf bank_mask:0xf bound_ctrl:1
	v_fma_f32 v18, v94, v161, v8
	ds_read_b128 v[124:127], v34 offset:7168
	v_add_f32_dpp v15, v15, v15 row_ror:4 row_mask:0xf bank_mask:0xf bound_ctrl:1
	ds_read_b128 v[128:131], v34 offset:7424
	ds_read_b128 v[132:135], v34 offset:7680
	v_add_f32_dpp v15, v15, v15 row_ror:2 row_mask:0xf bank_mask:0xf bound_ctrl:1
	v_fma_f32 v19, v95, v161, v9
	ds_read_b128 v[136:139], v34 offset:7936
	ds_read_b128 v[156:159], v35 offset:32
	v_add_f32_dpp v30, v15, v15 row_ror:1 row_mask:0xf bank_mask:0xf bound_ctrl:1
	v_pk_fma_f32 v[10:11], v[96:97], v[30:31], v[16:17] op_sel_hi:[1,0,1] neg_lo:[0,1,0] neg_hi:[0,1,0]
	v_pk_fma_f32 v[8:9], v[98:99], v[30:31], v[18:19] op_sel_hi:[1,0,1] neg_lo:[0,1,0] neg_hi:[0,1,0]
	v_pk_mul_f32 v[26:27], v[10:11], v[100:101] op_sel:[0,0] op_sel_hi:[0,1]
	v_pk_fma_f32 v[26:27], v[10:11], v[102:103], v[26:27] op_sel:[1,0,0] op_sel_hi:[1,1,1]
	v_pk_fma_f32 v[26:27], v[8:9], v[104:105], v[26:27] op_sel:[0,0,0] op_sel_hi:[0,1,1]
	v_pk_fma_f32 v[26:27], v[8:9], v[106:107], v[26:27] op_sel:[1,0,0] op_sel_hi:[1,1,1]
	v_fma_f32 v16, v108, v162, v10
	v_fma_f32 v17, v109, v162, v11
	v_add_f32_dpp v15, v26, v26 row_ror:8 row_mask:0xf bank_mask:0xf bound_ctrl:1
	v_fma_f32 v18, v110, v162, v8
	ds_read_b128 v[76:79], v34 offset:8192
	v_add_f32_dpp v15, v15, v15 row_ror:4 row_mask:0xf bank_mask:0xf bound_ctrl:1
	ds_read_b128 v[80:83], v34 offset:8448
	ds_read_b128 v[84:87], v34 offset:8704
	v_add_f32_dpp v15, v15, v15 row_ror:2 row_mask:0xf bank_mask:0xf bound_ctrl:1
	v_fma_f32 v19, v111, v162, v9
	ds_read_b128 v[88:91], v34 offset:8960
	ds_read_b128 v[144:147], v34 offset:33024
	ds_write2st64_b32 v37, v25, v27 offset0:16 offset1:20
	v_add_f32_dpp v30, v15, v15 row_ror:1 row_mask:0xf bank_mask:0xf bound_ctrl:1
	s_waitcnt lgkmcnt(5)
	v_pk_fma_f32 v[10:11], v[112:113], v[30:31], v[16:17] op_sel_hi:[1,0,1] neg_lo:[0,1,0] neg_hi:[0,1,0]
	v_pk_fma_f32 v[8:9], v[114:115], v[30:31], v[18:19] op_sel_hi:[1,0,1] neg_lo:[0,1,0] neg_hi:[0,1,0]
	v_pk_mul_f32 v[24:25], v[10:11], v[116:117] op_sel:[0,0] op_sel_hi:[0,1]
	v_pk_fma_f32 v[24:25], v[10:11], v[118:119], v[24:25] op_sel:[1,0,0] op_sel_hi:[1,1,1]
	v_pk_fma_f32 v[24:25], v[8:9], v[120:121], v[24:25] op_sel:[0,0,0] op_sel_hi:[0,1,1]
	v_pk_fma_f32 v[24:25], v[8:9], v[122:123], v[24:25] op_sel:[1,0,0] op_sel_hi:[1,1,1]
	v_fma_f32 v16, v124, v163, v10
	v_fma_f32 v17, v125, v163, v11
	v_add_f32_dpp v15, v24, v24 row_ror:8 row_mask:0xf bank_mask:0xf bound_ctrl:1
	v_fma_f32 v18, v126, v163, v8
	ds_read_b128 v[92:95], v34 offset:9216
	v_add_f32_dpp v15, v15, v15 row_ror:4 row_mask:0xf bank_mask:0xf bound_ctrl:1
	ds_read_b128 v[96:99], v34 offset:9472
	ds_read_b128 v[100:103], v34 offset:9728
	v_add_f32_dpp v15, v15, v15 row_ror:2 row_mask:0xf bank_mask:0xf bound_ctrl:1
	v_fma_f32 v19, v127, v163, v9
	ds_read_b128 v[104:107], v34 offset:9984
	v_add_f32_dpp v30, v15, v15 row_ror:1 row_mask:0xf bank_mask:0xf bound_ctrl:1
	v_pk_fma_f32 v[10:11], v[128:129], v[30:31], v[16:17] op_sel_hi:[1,0,1] neg_lo:[0,1,0] neg_hi:[0,1,0]
	v_pk_fma_f32 v[8:9], v[130:131], v[30:31], v[18:19] op_sel_hi:[1,0,1] neg_lo:[0,1,0] neg_hi:[0,1,0]
	v_pk_mul_f32 v[26:27], v[10:11], v[132:133] op_sel:[0,0] op_sel_hi:[0,1]
	v_pk_fma_f32 v[26:27], v[10:11], v[134:135], v[26:27] op_sel:[1,0,0] op_sel_hi:[1,1,1]
	v_pk_fma_f32 v[26:27], v[8:9], v[136:137], v[26:27] op_sel:[0,0,0] op_sel_hi:[0,1,1]
	v_pk_fma_f32 v[26:27], v[8:9], v[138:139], v[26:27] op_sel:[1,0,0] op_sel_hi:[1,1,1]
	ds_write2st64_b32 v37, v25, v27 offset0:24 offset1:28
	v_pk_mul_f32 v[10:11], v[10:11], v[140:141]
	v_pk_mul_f32 v[8:9], v[8:9], v[142:143]
	s_waitcnt lgkmcnt(6)
	v_pk_mul_f32 v[24:25], v[10:11], v[144:145]
	v_pk_fma_f32 v[24:25], v[8:9], v[146:147], v[24:25]
	v_add_f32_e32 v24, v24, v25
	v_fma_f32 v16, v76, v156, v10
	v_fma_f32 v17, v77, v156, v11
	v_add_f32_dpp v15, v24, v24 row_ror:8 row_mask:0xf bank_mask:0xf bound_ctrl:1
	v_fma_f32 v18, v78, v156, v8
	v_fma_f32 v19, v79, v156, v9
	v_add_f32_dpp v15, v15, v15 row_ror:4 row_mask:0xf bank_mask:0xf bound_ctrl:1
	ds_read_b128 v[108:111], v34 offset:10240
	ds_read_b128 v[112:115], v34 offset:10496
	v_add_f32_dpp v15, v15, v15 row_ror:2 row_mask:0xf bank_mask:0xf bound_ctrl:1
	ds_read_b128 v[116:119], v34 offset:10752
	ds_read_b128 v[120:123], v34 offset:11008
	v_add_f32_dpp v30, v15, v15 row_ror:1 row_mask:0xf bank_mask:0xf bound_ctrl:1
	s_waitcnt lgkmcnt(3)
	v_pk_fma_f32 v[10:11], v[80:81], v[30:31], v[16:17] op_sel_hi:[1,0,1] neg_lo:[0,1,0] neg_hi:[0,1,0]
	v_pk_fma_f32 v[8:9], v[82:83], v[30:31], v[18:19] op_sel_hi:[1,0,1] neg_lo:[0,1,0] neg_hi:[0,1,0]
	v_pk_mul_f32 v[24:25], v[10:11], v[84:85] op_sel:[0,0] op_sel_hi:[0,1]
	v_pk_fma_f32 v[24:25], v[10:11], v[86:87], v[24:25] op_sel:[1,0,0] op_sel_hi:[1,1,1]
	v_pk_fma_f32 v[24:25], v[8:9], v[88:89], v[24:25] op_sel:[0,0,0] op_sel_hi:[0,1,1]
	v_pk_fma_f32 v[24:25], v[8:9], v[90:91], v[24:25] op_sel:[1,0,0] op_sel_hi:[1,1,1]
	v_fma_f32 v16, v92, v157, v10
	v_fma_f32 v17, v93, v157, v11
	v_add_f32_dpp v15, v24, v24 row_ror:8 row_mask:0xf bank_mask:0xf bound_ctrl:1
	v_fma_f32 v18, v94, v157, v8
	ds_read_b128 v[124:127], v34 offset:11264
	v_add_f32_dpp v15, v15, v15 row_ror:4 row_mask:0xf bank_mask:0xf bound_ctrl:1
	ds_read_b128 v[128:131], v34 offset:11520
	ds_read_b128 v[132:135], v34 offset:11776
	v_add_f32_dpp v15, v15, v15 row_ror:2 row_mask:0xf bank_mask:0xf bound_ctrl:1
	v_fma_f32 v19, v95, v157, v9
	ds_read_b128 v[136:139], v34 offset:12032
	ds_read_b128 v[160:163], v35 offset:48
	v_add_f32_dpp v30, v15, v15 row_ror:1 row_mask:0xf bank_mask:0xf bound_ctrl:1
	v_pk_fma_f32 v[10:11], v[96:97], v[30:31], v[16:17] op_sel_hi:[1,0,1] neg_lo:[0,1,0] neg_hi:[0,1,0]
	v_pk_fma_f32 v[8:9], v[98:99], v[30:31], v[18:19] op_sel_hi:[1,0,1] neg_lo:[0,1,0] neg_hi:[0,1,0]
	v_pk_mul_f32 v[26:27], v[10:11], v[100:101] op_sel:[0,0] op_sel_hi:[0,1]
	v_pk_fma_f32 v[26:27], v[10:11], v[102:103], v[26:27] op_sel:[1,0,0] op_sel_hi:[1,1,1]
	v_pk_fma_f32 v[26:27], v[8:9], v[104:105], v[26:27] op_sel:[0,0,0] op_sel_hi:[0,1,1]
	v_pk_fma_f32 v[26:27], v[8:9], v[106:107], v[26:27] op_sel:[1,0,0] op_sel_hi:[1,1,1]
	v_fma_f32 v16, v108, v158, v10
	v_fma_f32 v17, v109, v158, v11
	v_add_f32_dpp v15, v26, v26 row_ror:8 row_mask:0xf bank_mask:0xf bound_ctrl:1
	v_fma_f32 v18, v110, v158, v8
	ds_read_b128 v[76:79], v34 offset:12288
	v_add_f32_dpp v15, v15, v15 row_ror:4 row_mask:0xf bank_mask:0xf bound_ctrl:1
	ds_read_b128 v[80:83], v34 offset:12544
	ds_read_b128 v[84:87], v34 offset:12800
	v_add_f32_dpp v15, v15, v15 row_ror:2 row_mask:0xf bank_mask:0xf bound_ctrl:1
	v_fma_f32 v19, v111, v158, v9
	ds_read_b128 v[88:91], v34 offset:13056
	ds_write2st64_b32 v37, v25, v27 offset0:32 offset1:36
	v_add_f32_dpp v30, v15, v15 row_ror:1 row_mask:0xf bank_mask:0xf bound_ctrl:1
	s_waitcnt lgkmcnt(4)
	v_pk_fma_f32 v[10:11], v[112:113], v[30:31], v[16:17] op_sel_hi:[1,0,1] neg_lo:[0,1,0] neg_hi:[0,1,0]
	v_pk_fma_f32 v[8:9], v[114:115], v[30:31], v[18:19] op_sel_hi:[1,0,1] neg_lo:[0,1,0] neg_hi:[0,1,0]
	v_pk_mul_f32 v[24:25], v[10:11], v[116:117] op_sel:[0,0] op_sel_hi:[0,1]
	v_pk_fma_f32 v[24:25], v[10:11], v[118:119], v[24:25] op_sel:[1,0,0] op_sel_hi:[1,1,1]
	v_pk_fma_f32 v[24:25], v[8:9], v[120:121], v[24:25] op_sel:[0,0,0] op_sel_hi:[0,1,1]
	v_pk_fma_f32 v[24:25], v[8:9], v[122:123], v[24:25] op_sel:[1,0,0] op_sel_hi:[1,1,1]
	v_fma_f32 v16, v124, v159, v10
	v_fma_f32 v17, v125, v159, v11
	v_add_f32_dpp v15, v24, v24 row_ror:8 row_mask:0xf bank_mask:0xf bound_ctrl:1
	v_fma_f32 v18, v126, v159, v8
	ds_read_b128 v[92:95], v34 offset:13312
	v_add_f32_dpp v15, v15, v15 row_ror:4 row_mask:0xf bank_mask:0xf bound_ctrl:1
	ds_read_b128 v[96:99], v34 offset:13568
	ds_read_b128 v[100:103], v34 offset:13824
	v_add_f32_dpp v15, v15, v15 row_ror:2 row_mask:0xf bank_mask:0xf bound_ctrl:1
	v_fma_f32 v19, v127, v159, v9
	ds_read_b128 v[104:107], v34 offset:14080
	v_add_f32_dpp v30, v15, v15 row_ror:1 row_mask:0xf bank_mask:0xf bound_ctrl:1
	v_pk_fma_f32 v[10:11], v[128:129], v[30:31], v[16:17] op_sel_hi:[1,0,1] neg_lo:[0,1,0] neg_hi:[0,1,0]
	v_pk_fma_f32 v[8:9], v[130:131], v[30:31], v[18:19] op_sel_hi:[1,0,1] neg_lo:[0,1,0] neg_hi:[0,1,0]
	v_pk_mul_f32 v[26:27], v[10:11], v[132:133] op_sel:[0,0] op_sel_hi:[0,1]
	v_pk_fma_f32 v[26:27], v[10:11], v[134:135], v[26:27] op_sel:[1,0,0] op_sel_hi:[1,1,1]
	v_pk_fma_f32 v[26:27], v[8:9], v[136:137], v[26:27] op_sel:[0,0,0] op_sel_hi:[0,1,1]
	v_pk_fma_f32 v[26:27], v[8:9], v[138:139], v[26:27] op_sel:[1,0,0] op_sel_hi:[1,1,1]
	v_fma_f32 v16, v76, v160, v10
	v_fma_f32 v17, v77, v160, v11
	v_add_f32_dpp v15, v26, v26 row_ror:8 row_mask:0xf bank_mask:0xf bound_ctrl:1
	v_fma_f32 v18, v78, v160, v8
	ds_read_b128 v[108:111], v34 offset:14336
	v_add_f32_dpp v15, v15, v15 row_ror:4 row_mask:0xf bank_mask:0xf bound_ctrl:1
	ds_read_b128 v[112:115], v34 offset:14592
	ds_read_b128 v[116:119], v34 offset:14848
	v_add_f32_dpp v15, v15, v15 row_ror:2 row_mask:0xf bank_mask:0xf bound_ctrl:1
	v_fma_f32 v19, v79, v160, v9
	ds_read_b128 v[120:123], v34 offset:15104
	ds_read_b128 v[140:143], v34 offset:34048
	ds_write2st64_b32 v37, v25, v27 offset0:40 offset1:44
	v_add_f32_dpp v30, v15, v15 row_ror:1 row_mask:0xf bank_mask:0xf bound_ctrl:1
	s_waitcnt lgkmcnt(5)
	v_pk_fma_f32 v[10:11], v[80:81], v[30:31], v[16:17] op_sel_hi:[1,0,1] neg_lo:[0,1,0] neg_hi:[0,1,0]
	v_pk_fma_f32 v[8:9], v[82:83], v[30:31], v[18:19] op_sel_hi:[1,0,1] neg_lo:[0,1,0] neg_hi:[0,1,0]
	v_pk_mul_f32 v[24:25], v[10:11], v[84:85] op_sel:[0,0] op_sel_hi:[0,1]
	v_pk_fma_f32 v[24:25], v[10:11], v[86:87], v[24:25] op_sel:[1,0,0] op_sel_hi:[1,1,1]
	v_pk_fma_f32 v[24:25], v[8:9], v[88:89], v[24:25] op_sel:[0,0,0] op_sel_hi:[0,1,1]
	v_pk_fma_f32 v[24:25], v[8:9], v[90:91], v[24:25] op_sel:[1,0,0] op_sel_hi:[1,1,1]
	v_fma_f32 v16, v92, v161, v10
	v_fma_f32 v17, v93, v161, v11
	v_add_f32_dpp v15, v24, v24 row_ror:8 row_mask:0xf bank_mask:0xf bound_ctrl:1
	v_fma_f32 v18, v94, v161, v8
	ds_read_b128 v[124:127], v34 offset:15360
	v_add_f32_dpp v15, v15, v15 row_ror:4 row_mask:0xf bank_mask:0xf bound_ctrl:1
	ds_read_b128 v[128:131], v34 offset:15616
	ds_read_b128 v[132:135], v34 offset:15872
	v_add_f32_dpp v15, v15, v15 row_ror:2 row_mask:0xf bank_mask:0xf bound_ctrl:1
	v_fma_f32 v19, v95, v161, v9
	ds_read_b128 v[136:139], v34 offset:16128
	ds_read_b128 v[156:159], v35 offset:64
	v_add_f32_dpp v30, v15, v15 row_ror:1 row_mask:0xf bank_mask:0xf bound_ctrl:1
	v_pk_fma_f32 v[10:11], v[96:97], v[30:31], v[16:17] op_sel_hi:[1,0,1] neg_lo:[0,1,0] neg_hi:[0,1,0]
	v_pk_fma_f32 v[8:9], v[98:99], v[30:31], v[18:19] op_sel_hi:[1,0,1] neg_lo:[0,1,0] neg_hi:[0,1,0]
	v_pk_mul_f32 v[26:27], v[10:11], v[100:101] op_sel:[0,0] op_sel_hi:[0,1]
	v_pk_fma_f32 v[26:27], v[10:11], v[102:103], v[26:27] op_sel:[1,0,0] op_sel_hi:[1,1,1]
	v_pk_fma_f32 v[26:27], v[8:9], v[104:105], v[26:27] op_sel:[0,0,0] op_sel_hi:[0,1,1]
	v_pk_fma_f32 v[26:27], v[8:9], v[106:107], v[26:27] op_sel:[1,0,0] op_sel_hi:[1,1,1]
	v_fma_f32 v16, v108, v162, v10
	v_fma_f32 v17, v109, v162, v11
	v_add_f32_dpp v15, v26, v26 row_ror:8 row_mask:0xf bank_mask:0xf bound_ctrl:1
	v_fma_f32 v18, v110, v162, v8
	ds_read_b128 v[76:79], v34 offset:16384
	v_add_f32_dpp v15, v15, v15 row_ror:4 row_mask:0xf bank_mask:0xf bound_ctrl:1
	ds_read_b128 v[80:83], v34 offset:16640
	ds_read_b128 v[84:87], v34 offset:16896
	v_add_f32_dpp v15, v15, v15 row_ror:2 row_mask:0xf bank_mask:0xf bound_ctrl:1
	v_fma_f32 v19, v111, v162, v9
	ds_read_b128 v[88:91], v34 offset:17152
	ds_read_b128 v[144:147], v34 offset:33280
	ds_write2st64_b32 v37, v25, v27 offset0:48 offset1:52
	v_add_f32_dpp v30, v15, v15 row_ror:1 row_mask:0xf bank_mask:0xf bound_ctrl:1
	s_waitcnt lgkmcnt(5)
	v_pk_fma_f32 v[10:11], v[112:113], v[30:31], v[16:17] op_sel_hi:[1,0,1] neg_lo:[0,1,0] neg_hi:[0,1,0]
	v_pk_fma_f32 v[8:9], v[114:115], v[30:31], v[18:19] op_sel_hi:[1,0,1] neg_lo:[0,1,0] neg_hi:[0,1,0]
	v_pk_mul_f32 v[24:25], v[10:11], v[116:117] op_sel:[0,0] op_sel_hi:[0,1]
	v_pk_fma_f32 v[24:25], v[10:11], v[118:119], v[24:25] op_sel:[1,0,0] op_sel_hi:[1,1,1]
	v_pk_fma_f32 v[24:25], v[8:9], v[120:121], v[24:25] op_sel:[0,0,0] op_sel_hi:[0,1,1]
	v_pk_fma_f32 v[24:25], v[8:9], v[122:123], v[24:25] op_sel:[1,0,0] op_sel_hi:[1,1,1]
	v_fma_f32 v16, v124, v163, v10
	v_fma_f32 v17, v125, v163, v11
	v_add_f32_dpp v15, v24, v24 row_ror:8 row_mask:0xf bank_mask:0xf bound_ctrl:1
	v_fma_f32 v18, v126, v163, v8
	ds_read_b128 v[92:95], v34 offset:17408
	v_add_f32_dpp v15, v15, v15 row_ror:4 row_mask:0xf bank_mask:0xf bound_ctrl:1
	ds_read_b128 v[96:99], v34 offset:17664
	ds_read_b128 v[100:103], v34 offset:17920
	v_add_f32_dpp v15, v15, v15 row_ror:2 row_mask:0xf bank_mask:0xf bound_ctrl:1
	v_fma_f32 v19, v127, v163, v9
	ds_read_b128 v[104:107], v34 offset:18176
	v_add_f32_dpp v30, v15, v15 row_ror:1 row_mask:0xf bank_mask:0xf bound_ctrl:1
	v_pk_fma_f32 v[10:11], v[128:129], v[30:31], v[16:17] op_sel_hi:[1,0,1] neg_lo:[0,1,0] neg_hi:[0,1,0]
	v_pk_fma_f32 v[8:9], v[130:131], v[30:31], v[18:19] op_sel_hi:[1,0,1] neg_lo:[0,1,0] neg_hi:[0,1,0]
	v_pk_mul_f32 v[26:27], v[10:11], v[132:133] op_sel:[0,0] op_sel_hi:[0,1]
	v_pk_fma_f32 v[26:27], v[10:11], v[134:135], v[26:27] op_sel:[1,0,0] op_sel_hi:[1,1,1]
	v_pk_fma_f32 v[26:27], v[8:9], v[136:137], v[26:27] op_sel:[0,0,0] op_sel_hi:[0,1,1]
	v_pk_fma_f32 v[26:27], v[8:9], v[138:139], v[26:27] op_sel:[1,0,0] op_sel_hi:[1,1,1]
	ds_write2st64_b32 v37, v25, v27 offset0:56 offset1:60
	v_pk_mul_f32 v[10:11], v[10:11], v[140:141]
	v_pk_mul_f32 v[8:9], v[8:9], v[142:143]
	s_waitcnt lgkmcnt(6)
	v_pk_mul_f32 v[24:25], v[10:11], v[144:145]
	v_pk_fma_f32 v[24:25], v[8:9], v[146:147], v[24:25]
	v_add_f32_e32 v24, v24, v25
	v_fma_f32 v16, v76, v156, v10
	v_fma_f32 v17, v77, v156, v11
	v_add_f32_dpp v15, v24, v24 row_ror:8 row_mask:0xf bank_mask:0xf bound_ctrl:1
	v_fma_f32 v18, v78, v156, v8
	v_fma_f32 v19, v79, v156, v9
	v_add_f32_dpp v15, v15, v15 row_ror:4 row_mask:0xf bank_mask:0xf bound_ctrl:1
	ds_read_b128 v[108:111], v34 offset:18432
	ds_read_b128 v[112:115], v34 offset:18688
	v_add_f32_dpp v15, v15, v15 row_ror:2 row_mask:0xf bank_mask:0xf bound_ctrl:1
	ds_read_b128 v[116:119], v34 offset:18944
	ds_read_b128 v[120:123], v34 offset:19200
	v_add_f32_dpp v30, v15, v15 row_ror:1 row_mask:0xf bank_mask:0xf bound_ctrl:1
	s_waitcnt lgkmcnt(3)
	v_pk_fma_f32 v[10:11], v[80:81], v[30:31], v[16:17] op_sel_hi:[1,0,1] neg_lo:[0,1,0] neg_hi:[0,1,0]
	v_pk_fma_f32 v[8:9], v[82:83], v[30:31], v[18:19] op_sel_hi:[1,0,1] neg_lo:[0,1,0] neg_hi:[0,1,0]
	v_pk_mul_f32 v[24:25], v[10:11], v[84:85] op_sel:[0,0] op_sel_hi:[0,1]
	v_pk_fma_f32 v[24:25], v[10:11], v[86:87], v[24:25] op_sel:[1,0,0] op_sel_hi:[1,1,1]
	v_pk_fma_f32 v[24:25], v[8:9], v[88:89], v[24:25] op_sel:[0,0,0] op_sel_hi:[0,1,1]
	v_pk_fma_f32 v[24:25], v[8:9], v[90:91], v[24:25] op_sel:[1,0,0] op_sel_hi:[1,1,1]
	v_fma_f32 v16, v92, v157, v10
	v_fma_f32 v17, v93, v157, v11
	v_add_f32_dpp v15, v24, v24 row_ror:8 row_mask:0xf bank_mask:0xf bound_ctrl:1
	v_fma_f32 v18, v94, v157, v8
	ds_read_b128 v[124:127], v34 offset:19456
	v_add_f32_dpp v15, v15, v15 row_ror:4 row_mask:0xf bank_mask:0xf bound_ctrl:1
	ds_read_b128 v[128:131], v34 offset:19712
	ds_read_b128 v[132:135], v34 offset:19968
	v_add_f32_dpp v15, v15, v15 row_ror:2 row_mask:0xf bank_mask:0xf bound_ctrl:1
	v_fma_f32 v19, v95, v157, v9
	ds_read_b128 v[136:139], v34 offset:20224
	ds_read_b128 v[160:163], v35 offset:80
	v_add_f32_dpp v30, v15, v15 row_ror:1 row_mask:0xf bank_mask:0xf bound_ctrl:1
	v_pk_fma_f32 v[10:11], v[96:97], v[30:31], v[16:17] op_sel_hi:[1,0,1] neg_lo:[0,1,0] neg_hi:[0,1,0]
	v_pk_fma_f32 v[8:9], v[98:99], v[30:31], v[18:19] op_sel_hi:[1,0,1] neg_lo:[0,1,0] neg_hi:[0,1,0]
	v_pk_mul_f32 v[26:27], v[10:11], v[100:101] op_sel:[0,0] op_sel_hi:[0,1]
	v_pk_fma_f32 v[26:27], v[10:11], v[102:103], v[26:27] op_sel:[1,0,0] op_sel_hi:[1,1,1]
	v_pk_fma_f32 v[26:27], v[8:9], v[104:105], v[26:27] op_sel:[0,0,0] op_sel_hi:[0,1,1]
	v_pk_fma_f32 v[26:27], v[8:9], v[106:107], v[26:27] op_sel:[1,0,0] op_sel_hi:[1,1,1]
	v_fma_f32 v16, v108, v158, v10
	v_fma_f32 v17, v109, v158, v11
	v_add_f32_dpp v15, v26, v26 row_ror:8 row_mask:0xf bank_mask:0xf bound_ctrl:1
	v_fma_f32 v18, v110, v158, v8
	ds_read_b128 v[76:79], v34 offset:20480
	v_add_f32_dpp v15, v15, v15 row_ror:4 row_mask:0xf bank_mask:0xf bound_ctrl:1
	ds_read_b128 v[80:83], v34 offset:20736
	ds_read_b128 v[84:87], v34 offset:20992
	v_add_f32_dpp v15, v15, v15 row_ror:2 row_mask:0xf bank_mask:0xf bound_ctrl:1
	v_fma_f32 v19, v111, v158, v9
	ds_read_b128 v[88:91], v34 offset:21248
	ds_write2st64_b32 v37, v25, v27 offset0:64 offset1:68
	v_add_f32_dpp v30, v15, v15 row_ror:1 row_mask:0xf bank_mask:0xf bound_ctrl:1
	s_waitcnt lgkmcnt(4)
	v_pk_fma_f32 v[10:11], v[112:113], v[30:31], v[16:17] op_sel_hi:[1,0,1] neg_lo:[0,1,0] neg_hi:[0,1,0]
	v_pk_fma_f32 v[8:9], v[114:115], v[30:31], v[18:19] op_sel_hi:[1,0,1] neg_lo:[0,1,0] neg_hi:[0,1,0]
	v_pk_mul_f32 v[24:25], v[10:11], v[116:117] op_sel:[0,0] op_sel_hi:[0,1]
	v_pk_fma_f32 v[24:25], v[10:11], v[118:119], v[24:25] op_sel:[1,0,0] op_sel_hi:[1,1,1]
	v_pk_fma_f32 v[24:25], v[8:9], v[120:121], v[24:25] op_sel:[0,0,0] op_sel_hi:[0,1,1]
	v_pk_fma_f32 v[24:25], v[8:9], v[122:123], v[24:25] op_sel:[1,0,0] op_sel_hi:[1,1,1]
	v_fma_f32 v16, v124, v159, v10
	v_fma_f32 v17, v125, v159, v11
	v_add_f32_dpp v15, v24, v24 row_ror:8 row_mask:0xf bank_mask:0xf bound_ctrl:1
	v_fma_f32 v18, v126, v159, v8
	ds_read_b128 v[92:95], v34 offset:21504
	v_add_f32_dpp v15, v15, v15 row_ror:4 row_mask:0xf bank_mask:0xf bound_ctrl:1
	ds_read_b128 v[96:99], v34 offset:21760
	ds_read_b128 v[100:103], v34 offset:22016
	v_add_f32_dpp v15, v15, v15 row_ror:2 row_mask:0xf bank_mask:0xf bound_ctrl:1
	v_fma_f32 v19, v127, v159, v9
	ds_read_b128 v[104:107], v34 offset:22272
	v_add_f32_dpp v30, v15, v15 row_ror:1 row_mask:0xf bank_mask:0xf bound_ctrl:1
	v_pk_fma_f32 v[10:11], v[128:129], v[30:31], v[16:17] op_sel_hi:[1,0,1] neg_lo:[0,1,0] neg_hi:[0,1,0]
	v_pk_fma_f32 v[8:9], v[130:131], v[30:31], v[18:19] op_sel_hi:[1,0,1] neg_lo:[0,1,0] neg_hi:[0,1,0]
	v_pk_mul_f32 v[26:27], v[10:11], v[132:133] op_sel:[0,0] op_sel_hi:[0,1]
	v_pk_fma_f32 v[26:27], v[10:11], v[134:135], v[26:27] op_sel:[1,0,0] op_sel_hi:[1,1,1]
	v_pk_fma_f32 v[26:27], v[8:9], v[136:137], v[26:27] op_sel:[0,0,0] op_sel_hi:[0,1,1]
	v_pk_fma_f32 v[26:27], v[8:9], v[138:139], v[26:27] op_sel:[1,0,0] op_sel_hi:[1,1,1]
	v_fma_f32 v16, v76, v160, v10
	v_fma_f32 v17, v77, v160, v11
	v_add_f32_dpp v15, v26, v26 row_ror:8 row_mask:0xf bank_mask:0xf bound_ctrl:1
	v_fma_f32 v18, v78, v160, v8
	ds_read_b128 v[108:111], v34 offset:22528
	v_add_f32_dpp v15, v15, v15 row_ror:4 row_mask:0xf bank_mask:0xf bound_ctrl:1
	ds_read_b128 v[112:115], v34 offset:22784
	ds_read_b128 v[116:119], v34 offset:23040
	v_add_f32_dpp v15, v15, v15 row_ror:2 row_mask:0xf bank_mask:0xf bound_ctrl:1
	v_fma_f32 v19, v79, v160, v9
	ds_read_b128 v[120:123], v34 offset:23296
	ds_read_b128 v[140:143], v34 offset:34304
	ds_write2st64_b32 v37, v25, v27 offset0:72 offset1:76
	v_add_f32_dpp v30, v15, v15 row_ror:1 row_mask:0xf bank_mask:0xf bound_ctrl:1
	s_waitcnt lgkmcnt(5)
	v_pk_fma_f32 v[10:11], v[80:81], v[30:31], v[16:17] op_sel_hi:[1,0,1] neg_lo:[0,1,0] neg_hi:[0,1,0]
	v_pk_fma_f32 v[8:9], v[82:83], v[30:31], v[18:19] op_sel_hi:[1,0,1] neg_lo:[0,1,0] neg_hi:[0,1,0]
	v_pk_mul_f32 v[24:25], v[10:11], v[84:85] op_sel:[0,0] op_sel_hi:[0,1]
	v_pk_fma_f32 v[24:25], v[10:11], v[86:87], v[24:25] op_sel:[1,0,0] op_sel_hi:[1,1,1]
	v_pk_fma_f32 v[24:25], v[8:9], v[88:89], v[24:25] op_sel:[0,0,0] op_sel_hi:[0,1,1]
	v_pk_fma_f32 v[24:25], v[8:9], v[90:91], v[24:25] op_sel:[1,0,0] op_sel_hi:[1,1,1]
	v_fma_f32 v16, v92, v161, v10
	v_fma_f32 v17, v93, v161, v11
	v_add_f32_dpp v15, v24, v24 row_ror:8 row_mask:0xf bank_mask:0xf bound_ctrl:1
	v_fma_f32 v18, v94, v161, v8
	ds_read_b128 v[124:127], v34 offset:23552
	v_add_f32_dpp v15, v15, v15 row_ror:4 row_mask:0xf bank_mask:0xf bound_ctrl:1
	ds_read_b128 v[128:131], v34 offset:23808
	ds_read_b128 v[132:135], v34 offset:24064
	v_add_f32_dpp v15, v15, v15 row_ror:2 row_mask:0xf bank_mask:0xf bound_ctrl:1
	v_fma_f32 v19, v95, v161, v9
	ds_read_b128 v[136:139], v34 offset:24320
	ds_read_b128 v[156:159], v35 offset:96
	v_add_f32_dpp v30, v15, v15 row_ror:1 row_mask:0xf bank_mask:0xf bound_ctrl:1
	v_pk_fma_f32 v[10:11], v[96:97], v[30:31], v[16:17] op_sel_hi:[1,0,1] neg_lo:[0,1,0] neg_hi:[0,1,0]
	v_pk_fma_f32 v[8:9], v[98:99], v[30:31], v[18:19] op_sel_hi:[1,0,1] neg_lo:[0,1,0] neg_hi:[0,1,0]
	v_pk_mul_f32 v[26:27], v[10:11], v[100:101] op_sel:[0,0] op_sel_hi:[0,1]
	v_pk_fma_f32 v[26:27], v[10:11], v[102:103], v[26:27] op_sel:[1,0,0] op_sel_hi:[1,1,1]
	v_pk_fma_f32 v[26:27], v[8:9], v[104:105], v[26:27] op_sel:[0,0,0] op_sel_hi:[0,1,1]
	v_pk_fma_f32 v[26:27], v[8:9], v[106:107], v[26:27] op_sel:[1,0,0] op_sel_hi:[1,1,1]
	v_fma_f32 v16, v108, v162, v10
	v_fma_f32 v17, v109, v162, v11
	v_add_f32_dpp v15, v26, v26 row_ror:8 row_mask:0xf bank_mask:0xf bound_ctrl:1
	v_fma_f32 v18, v110, v162, v8
	ds_read_b128 v[76:79], v34 offset:24576
	v_add_f32_dpp v15, v15, v15 row_ror:4 row_mask:0xf bank_mask:0xf bound_ctrl:1
	ds_read_b128 v[80:83], v34 offset:24832
	ds_read_b128 v[84:87], v34 offset:25088
	v_add_f32_dpp v15, v15, v15 row_ror:2 row_mask:0xf bank_mask:0xf bound_ctrl:1
	v_fma_f32 v19, v111, v162, v9
	ds_read_b128 v[88:91], v34 offset:25344
	ds_read_b128 v[144:147], v34 offset:33536
	ds_write2st64_b32 v37, v25, v27 offset0:80 offset1:84
	v_add_f32_dpp v30, v15, v15 row_ror:1 row_mask:0xf bank_mask:0xf bound_ctrl:1
	s_waitcnt lgkmcnt(5)
	v_pk_fma_f32 v[10:11], v[112:113], v[30:31], v[16:17] op_sel_hi:[1,0,1] neg_lo:[0,1,0] neg_hi:[0,1,0]
	v_pk_fma_f32 v[8:9], v[114:115], v[30:31], v[18:19] op_sel_hi:[1,0,1] neg_lo:[0,1,0] neg_hi:[0,1,0]
	v_pk_mul_f32 v[24:25], v[10:11], v[116:117] op_sel:[0,0] op_sel_hi:[0,1]
	v_pk_fma_f32 v[24:25], v[10:11], v[118:119], v[24:25] op_sel:[1,0,0] op_sel_hi:[1,1,1]
	v_pk_fma_f32 v[24:25], v[8:9], v[120:121], v[24:25] op_sel:[0,0,0] op_sel_hi:[0,1,1]
	v_pk_fma_f32 v[24:25], v[8:9], v[122:123], v[24:25] op_sel:[1,0,0] op_sel_hi:[1,1,1]
	v_fma_f32 v16, v124, v163, v10
	v_fma_f32 v17, v125, v163, v11
	v_add_f32_dpp v15, v24, v24 row_ror:8 row_mask:0xf bank_mask:0xf bound_ctrl:1
	v_fma_f32 v18, v126, v163, v8
	ds_read_b128 v[92:95], v34 offset:25600
	v_add_f32_dpp v15, v15, v15 row_ror:4 row_mask:0xf bank_mask:0xf bound_ctrl:1
	ds_read_b128 v[96:99], v34 offset:25856
	ds_read_b128 v[100:103], v34 offset:26112
	v_add_f32_dpp v15, v15, v15 row_ror:2 row_mask:0xf bank_mask:0xf bound_ctrl:1
	v_fma_f32 v19, v127, v163, v9
	ds_read_b128 v[104:107], v34 offset:26368
	v_add_f32_dpp v30, v15, v15 row_ror:1 row_mask:0xf bank_mask:0xf bound_ctrl:1
	v_pk_fma_f32 v[10:11], v[128:129], v[30:31], v[16:17] op_sel_hi:[1,0,1] neg_lo:[0,1,0] neg_hi:[0,1,0]
	v_pk_fma_f32 v[8:9], v[130:131], v[30:31], v[18:19] op_sel_hi:[1,0,1] neg_lo:[0,1,0] neg_hi:[0,1,0]
	v_pk_mul_f32 v[26:27], v[10:11], v[132:133] op_sel:[0,0] op_sel_hi:[0,1]
	v_pk_fma_f32 v[26:27], v[10:11], v[134:135], v[26:27] op_sel:[1,0,0] op_sel_hi:[1,1,1]
	v_pk_fma_f32 v[26:27], v[8:9], v[136:137], v[26:27] op_sel:[0,0,0] op_sel_hi:[0,1,1]
	v_pk_fma_f32 v[26:27], v[8:9], v[138:139], v[26:27] op_sel:[1,0,0] op_sel_hi:[1,1,1]
	ds_write2st64_b32 v37, v25, v27 offset0:88 offset1:92
	v_pk_mul_f32 v[10:11], v[10:11], v[140:141]
	v_pk_mul_f32 v[8:9], v[8:9], v[142:143]
	s_waitcnt lgkmcnt(6)
	v_pk_mul_f32 v[24:25], v[10:11], v[144:145]
	v_pk_fma_f32 v[24:25], v[8:9], v[146:147], v[24:25]
	v_add_f32_e32 v24, v24, v25
	v_fma_f32 v16, v76, v156, v10
	v_fma_f32 v17, v77, v156, v11
	v_add_f32_dpp v15, v24, v24 row_ror:8 row_mask:0xf bank_mask:0xf bound_ctrl:1
	v_fma_f32 v18, v78, v156, v8
	v_fma_f32 v19, v79, v156, v9
	v_add_f32_dpp v15, v15, v15 row_ror:4 row_mask:0xf bank_mask:0xf bound_ctrl:1
	ds_read_b128 v[108:111], v34 offset:26624
	ds_read_b128 v[112:115], v34 offset:26880
	v_add_f32_dpp v15, v15, v15 row_ror:2 row_mask:0xf bank_mask:0xf bound_ctrl:1
	ds_read_b128 v[116:119], v34 offset:27136
	ds_read_b128 v[120:123], v34 offset:27392
	v_add_f32_dpp v30, v15, v15 row_ror:1 row_mask:0xf bank_mask:0xf bound_ctrl:1
	s_waitcnt lgkmcnt(3)
	v_pk_fma_f32 v[10:11], v[80:81], v[30:31], v[16:17] op_sel_hi:[1,0,1] neg_lo:[0,1,0] neg_hi:[0,1,0]
	v_pk_fma_f32 v[8:9], v[82:83], v[30:31], v[18:19] op_sel_hi:[1,0,1] neg_lo:[0,1,0] neg_hi:[0,1,0]
	v_pk_mul_f32 v[24:25], v[10:11], v[84:85] op_sel:[0,0] op_sel_hi:[0,1]
	v_pk_fma_f32 v[24:25], v[10:11], v[86:87], v[24:25] op_sel:[1,0,0] op_sel_hi:[1,1,1]
	v_pk_fma_f32 v[24:25], v[8:9], v[88:89], v[24:25] op_sel:[0,0,0] op_sel_hi:[0,1,1]
	v_pk_fma_f32 v[24:25], v[8:9], v[90:91], v[24:25] op_sel:[1,0,0] op_sel_hi:[1,1,1]
	v_fma_f32 v16, v92, v157, v10
	v_fma_f32 v17, v93, v157, v11
	v_add_f32_dpp v15, v24, v24 row_ror:8 row_mask:0xf bank_mask:0xf bound_ctrl:1
	v_fma_f32 v18, v94, v157, v8
	ds_read_b128 v[124:127], v34 offset:27648
	v_add_f32_dpp v15, v15, v15 row_ror:4 row_mask:0xf bank_mask:0xf bound_ctrl:1
	ds_read_b128 v[128:131], v34 offset:27904
	ds_read_b128 v[132:135], v34 offset:28160
	v_add_f32_dpp v15, v15, v15 row_ror:2 row_mask:0xf bank_mask:0xf bound_ctrl:1
	v_fma_f32 v19, v95, v157, v9
	ds_read_b128 v[136:139], v34 offset:28416
	ds_read_b128 v[160:163], v35 offset:112
	v_add_f32_dpp v30, v15, v15 row_ror:1 row_mask:0xf bank_mask:0xf bound_ctrl:1
	v_pk_fma_f32 v[10:11], v[96:97], v[30:31], v[16:17] op_sel_hi:[1,0,1] neg_lo:[0,1,0] neg_hi:[0,1,0]
	v_pk_fma_f32 v[8:9], v[98:99], v[30:31], v[18:19] op_sel_hi:[1,0,1] neg_lo:[0,1,0] neg_hi:[0,1,0]
	v_pk_mul_f32 v[26:27], v[10:11], v[100:101] op_sel:[0,0] op_sel_hi:[0,1]
	v_pk_fma_f32 v[26:27], v[10:11], v[102:103], v[26:27] op_sel:[1,0,0] op_sel_hi:[1,1,1]
	v_pk_fma_f32 v[26:27], v[8:9], v[104:105], v[26:27] op_sel:[0,0,0] op_sel_hi:[0,1,1]
	v_pk_fma_f32 v[26:27], v[8:9], v[106:107], v[26:27] op_sel:[1,0,0] op_sel_hi:[1,1,1]
	v_fma_f32 v16, v108, v158, v10
	v_fma_f32 v17, v109, v158, v11
	v_add_f32_dpp v15, v26, v26 row_ror:8 row_mask:0xf bank_mask:0xf bound_ctrl:1
	v_fma_f32 v18, v110, v158, v8
	ds_read_b128 v[76:79], v34 offset:28672
	v_add_f32_dpp v15, v15, v15 row_ror:4 row_mask:0xf bank_mask:0xf bound_ctrl:1
	ds_read_b128 v[80:83], v34 offset:28928
	ds_read_b128 v[84:87], v34 offset:29184
	v_add_f32_dpp v15, v15, v15 row_ror:2 row_mask:0xf bank_mask:0xf bound_ctrl:1
	v_fma_f32 v19, v111, v158, v9
	ds_read_b128 v[88:91], v34 offset:29440
	ds_write2st64_b32 v37, v25, v27 offset0:96 offset1:100
	v_add_f32_dpp v30, v15, v15 row_ror:1 row_mask:0xf bank_mask:0xf bound_ctrl:1
	ds_read_b128 v[56:59], v52
	s_waitcnt lgkmcnt(5)
	v_pk_fma_f32 v[10:11], v[112:113], v[30:31], v[16:17] op_sel_hi:[1,0,1] neg_lo:[0,1,0] neg_hi:[0,1,0]
	v_pk_fma_f32 v[8:9], v[114:115], v[30:31], v[18:19] op_sel_hi:[1,0,1] neg_lo:[0,1,0] neg_hi:[0,1,0]
	v_pk_mul_f32 v[24:25], v[10:11], v[116:117] op_sel:[0,0] op_sel_hi:[0,1]
	v_pk_fma_f32 v[24:25], v[10:11], v[118:119], v[24:25] op_sel:[1,0,0] op_sel_hi:[1,1,1]
	v_pk_fma_f32 v[24:25], v[8:9], v[120:121], v[24:25] op_sel:[0,0,0] op_sel_hi:[0,1,1]
	v_pk_fma_f32 v[24:25], v[8:9], v[122:123], v[24:25] op_sel:[1,0,0] op_sel_hi:[1,1,1]
	v_fma_f32 v16, v124, v159, v10
	v_fma_f32 v17, v125, v159, v11
	v_add_f32_dpp v15, v24, v24 row_ror:8 row_mask:0xf bank_mask:0xf bound_ctrl:1
	v_fma_f32 v18, v126, v159, v8
	ds_read_b128 v[92:95], v34 offset:29696
	v_add_f32_dpp v15, v15, v15 row_ror:4 row_mask:0xf bank_mask:0xf bound_ctrl:1
	ds_read_b128 v[96:99], v34 offset:29952
	ds_read_b128 v[100:103], v34 offset:30208
	v_add_f32_dpp v15, v15, v15 row_ror:2 row_mask:0xf bank_mask:0xf bound_ctrl:1
	v_fma_f32 v19, v127, v159, v9
	ds_read_b128 v[104:107], v34 offset:30464
	v_add_f32_dpp v30, v15, v15 row_ror:1 row_mask:0xf bank_mask:0xf bound_ctrl:1
	s_waitcnt lgkmcnt(4)
	v_min_u32_e32 v56, v56, v57
	v_min3_u32 v56, v56, v58, v59
	v_pk_fma_f32 v[10:11], v[128:129], v[30:31], v[16:17] op_sel_hi:[1,0,1] neg_lo:[0,1,0] neg_hi:[0,1,0]
	v_pk_fma_f32 v[8:9], v[130:131], v[30:31], v[18:19] op_sel_hi:[1,0,1] neg_lo:[0,1,0] neg_hi:[0,1,0]
	v_pk_mul_f32 v[26:27], v[10:11], v[132:133] op_sel:[0,0] op_sel_hi:[0,1]
	v_pk_fma_f32 v[26:27], v[10:11], v[134:135], v[26:27] op_sel:[1,0,0] op_sel_hi:[1,1,1]
	v_pk_fma_f32 v[26:27], v[8:9], v[136:137], v[26:27] op_sel:[0,0,0] op_sel_hi:[0,1,1]
	v_pk_fma_f32 v[26:27], v[8:9], v[138:139], v[26:27] op_sel:[1,0,0] op_sel_hi:[1,1,1]
	v_fma_f32 v16, v76, v160, v10
	v_fma_f32 v17, v77, v160, v11
	v_add_f32_dpp v15, v26, v26 row_ror:8 row_mask:0xf bank_mask:0xf bound_ctrl:1
	v_fma_f32 v18, v78, v160, v8
	ds_read_b128 v[108:111], v34 offset:30720
	v_add_f32_dpp v15, v15, v15 row_ror:4 row_mask:0xf bank_mask:0xf bound_ctrl:1
	ds_read_b128 v[112:115], v34 offset:30976
	ds_read_b128 v[116:119], v34 offset:31232
	v_add_f32_dpp v15, v15, v15 row_ror:2 row_mask:0xf bank_mask:0xf bound_ctrl:1
	v_fma_f32 v19, v79, v160, v9
	ds_read_b128 v[120:123], v34 offset:31488
	ds_read_b128 v[140:143], v34 offset:34560
	ds_write2st64_b32 v37, v25, v27 offset0:104 offset1:108
	v_add_f32_dpp v30, v15, v15 row_ror:1 row_mask:0xf bank_mask:0xf bound_ctrl:1
	s_waitcnt lgkmcnt(5)
	v_pk_fma_f32 v[10:11], v[80:81], v[30:31], v[16:17] op_sel_hi:[1,0,1] neg_lo:[0,1,0] neg_hi:[0,1,0]
	v_pk_fma_f32 v[8:9], v[82:83], v[30:31], v[18:19] op_sel_hi:[1,0,1] neg_lo:[0,1,0] neg_hi:[0,1,0]
	v_pk_mul_f32 v[24:25], v[10:11], v[84:85] op_sel:[0,0] op_sel_hi:[0,1]
	v_pk_fma_f32 v[24:25], v[10:11], v[86:87], v[24:25] op_sel:[1,0,0] op_sel_hi:[1,1,1]
	v_pk_fma_f32 v[24:25], v[8:9], v[88:89], v[24:25] op_sel:[0,0,0] op_sel_hi:[0,1,1]
	v_pk_fma_f32 v[24:25], v[8:9], v[90:91], v[24:25] op_sel:[1,0,0] op_sel_hi:[1,1,1]
	v_fma_f32 v16, v92, v161, v10
	v_fma_f32 v17, v93, v161, v11
	v_add_f32_dpp v15, v24, v24 row_ror:8 row_mask:0xf bank_mask:0xf bound_ctrl:1
	v_fma_f32 v18, v94, v161, v8
	ds_read_b128 v[124:127], v34 offset:31744
	v_add_f32_dpp v15, v15, v15 row_ror:4 row_mask:0xf bank_mask:0xf bound_ctrl:1
	ds_read_b128 v[128:131], v34 offset:32000
	ds_read_b128 v[132:135], v34 offset:32256
	v_add_f32_dpp v15, v15, v15 row_ror:2 row_mask:0xf bank_mask:0xf bound_ctrl:1
	v_fma_f32 v19, v95, v161, v9
	ds_read_b128 v[136:139], v34 offset:32512
	v_add_f32_dpp v30, v15, v15 row_ror:1 row_mask:0xf bank_mask:0xf bound_ctrl:1
	v_readfirstlane_b32 s54, v56
	s_add_u32 s64, s6, 2
	s_cmp_lt_u32 s54, s64
	s_cbranch_scc1 .Lss_spin_0
.Lss_ok_0:
	v_pk_fma_f32 v[10:11], v[96:97], v[30:31], v[16:17] op_sel_hi:[1,0,1] neg_lo:[0,1,0] neg_hi:[0,1,0]
	v_pk_fma_f32 v[8:9], v[98:99], v[30:31], v[18:19] op_sel_hi:[1,0,1] neg_lo:[0,1,0] neg_hi:[0,1,0]
	v_pk_mul_f32 v[26:27], v[10:11], v[100:101] op_sel:[0,0] op_sel_hi:[0,1]
	v_pk_fma_f32 v[26:27], v[10:11], v[102:103], v[26:27] op_sel:[1,0,0] op_sel_hi:[1,1,1]
	v_pk_fma_f32 v[26:27], v[8:9], v[104:105], v[26:27] op_sel:[0,0,0] op_sel_hi:[0,1,1]
	v_pk_fma_f32 v[26:27], v[8:9], v[106:107], v[26:27] op_sel:[1,0,0] op_sel_hi:[1,1,1]
	v_fma_f32 v16, v108, v162, v10
	v_fma_f32 v17, v109, v162, v11
	v_add_f32_dpp v15, v26, v26 row_ror:8 row_mask:0xf bank_mask:0xf bound_ctrl:1
	v_fma_f32 v18, v110, v162, v8
	ds_read_b128 v[76:79], v48 offset:0
	v_add_f32_dpp v15, v15, v15 row_ror:4 row_mask:0xf bank_mask:0xf bound_ctrl:1
	ds_read_b128 v[80:83], v48 offset:256
	ds_read_b128 v[84:87], v48 offset:512
	v_add_f32_dpp v15, v15, v15 row_ror:2 row_mask:0xf bank_mask:0xf bound_ctrl:1
	v_fma_f32 v19, v111, v162, v9
	ds_read_b128 v[88:91], v48 offset:768
	ds_read_b128 v[144:147], v48 offset:32768
	ds_write2st64_b32 v37, v25, v27 offset0:112 offset1:116
	v_add_f32_dpp v30, v15, v15 row_ror:1 row_mask:0xf bank_mask:0xf bound_ctrl:1
	ds_read_b128 v[156:159], v49 offset:0
	s_waitcnt lgkmcnt(6)
	v_pk_fma_f32 v[10:11], v[112:113], v[30:31], v[16:17] op_sel_hi:[1,0,1] neg_lo:[0,1,0] neg_hi:[0,1,0]
	v_pk_fma_f32 v[8:9], v[114:115], v[30:31], v[18:19] op_sel_hi:[1,0,1] neg_lo:[0,1,0] neg_hi:[0,1,0]
	v_pk_mul_f32 v[24:25], v[10:11], v[116:117] op_sel:[0,0] op_sel_hi:[0,1]
	v_pk_fma_f32 v[24:25], v[10:11], v[118:119], v[24:25] op_sel:[1,0,0] op_sel_hi:[1,1,1]
	v_pk_fma_f32 v[24:25], v[8:9], v[120:121], v[24:25] op_sel:[0,0,0] op_sel_hi:[0,1,1]
	v_pk_fma_f32 v[24:25], v[8:9], v[122:123], v[24:25] op_sel:[1,0,0] op_sel_hi:[1,1,1]
	v_fma_f32 v16, v124, v163, v10
	v_fma_f32 v17, v125, v163, v11
	v_add_f32_dpp v15, v24, v24 row_ror:8 row_mask:0xf bank_mask:0xf bound_ctrl:1
	v_fma_f32 v18, v126, v163, v8
	ds_read_b128 v[92:95], v48 offset:1024
	v_add_f32_dpp v15, v15, v15 row_ror:4 row_mask:0xf bank_mask:0xf bound_ctrl:1
	ds_read_b128 v[96:99], v48 offset:1280
	ds_read_b128 v[100:103], v48 offset:1536
	v_add_f32_dpp v15, v15, v15 row_ror:2 row_mask:0xf bank_mask:0xf bound_ctrl:1
	v_fma_f32 v19, v127, v163, v9
	ds_read_b128 v[104:107], v48 offset:1792
	v_add_f32_dpp v30, v15, v15 row_ror:1 row_mask:0xf bank_mask:0xf bound_ctrl:1
	v_pk_fma_f32 v[10:11], v[128:129], v[30:31], v[16:17] op_sel_hi:[1,0,1] neg_lo:[0,1,0] neg_hi:[0,1,0]
	v_pk_fma_f32 v[8:9], v[130:131], v[30:31], v[18:19] op_sel_hi:[1,0,1] neg_lo:[0,1,0] neg_hi:[0,1,0]
	v_pk_mul_f32 v[26:27], v[10:11], v[132:133] op_sel:[0,0] op_sel_hi:[0,1]
	v_pk_fma_f32 v[26:27], v[10:11], v[134:135], v[26:27] op_sel:[1,0,0] op_sel_hi:[1,1,1]
	v_pk_fma_f32 v[26:27], v[8:9], v[136:137], v[26:27] op_sel:[0,0,0] op_sel_hi:[0,1,1]
	v_pk_fma_f32 v[26:27], v[8:9], v[138:139], v[26:27] op_sel:[1,0,0] op_sel_hi:[1,1,1]
	ds_write2st64_b32 v37, v25, v27 offset0:120 offset1:124
	v_pk_mul_f32 v[10:11], v[10:11], v[140:141]
	v_pk_mul_f32 v[8:9], v[8:9], v[142:143]
	s_waitcnt lgkmcnt(7)
	v_pk_mul_f32 v[24:25], v[10:11], v[144:145]
	v_pk_fma_f32 v[24:25], v[8:9], v[146:147], v[24:25]
	v_add_f32_e32 v24, v24, v25
	s_waitcnt lgkmcnt(5)
	v_fma_f32 v16, v76, v156, v10
	v_fma_f32 v17, v77, v156, v11
	v_add_f32_dpp v15, v24, v24 row_ror:8 row_mask:0xf bank_mask:0xf bound_ctrl:1
	v_add_u32_e32 v51, 1, v51
	s_add_u32 s6, s6, 1
	v_add_f32_dpp v15, v15, v15 row_ror:4 row_mask:0xf bank_mask:0xf bound_ctrl:1
	ds_write_b32 v53, v51
	v_fma_f32 v18, v78, v156, v8
	v_add_f32_dpp v15, v15, v15 row_ror:2 row_mask:0xf bank_mask:0xf bound_ctrl:1
	v_fma_f32 v19, v79, v156, v9
	ds_read_b128 v[108:111], v48 offset:2048
	v_add_f32_dpp v30, v15, v15 row_ror:1 row_mask:0xf bank_mask:0xf bound_ctrl:1
	ds_read_b128 v[112:115], v48 offset:2304
	ds_read_b128 v[116:119], v48 offset:2560
	ds_read_b128 v[120:123], v48 offset:2816
	s_waitcnt lgkmcnt(3)
	v_pk_fma_f32 v[10:11], v[80:81], v[30:31], v[16:17] op_sel_hi:[1,0,1] neg_lo:[0,1,0] neg_hi:[0,1,0]
	v_pk_fma_f32 v[8:9], v[82:83], v[30:31], v[18:19] op_sel_hi:[1,0,1] neg_lo:[0,1,0] neg_hi:[0,1,0]
	v_pk_mul_f32 v[24:25], v[10:11], v[84:85] op_sel:[0,0] op_sel_hi:[0,1]
	v_pk_fma_f32 v[24:25], v[10:11], v[86:87], v[24:25] op_sel:[1,0,0] op_sel_hi:[1,1,1]
	v_pk_fma_f32 v[24:25], v[8:9], v[88:89], v[24:25] op_sel:[0,0,0] op_sel_hi:[0,1,1]
	v_pk_fma_f32 v[24:25], v[8:9], v[90:91], v[24:25] op_sel:[1,0,0] op_sel_hi:[1,1,1]
	v_fma_f32 v16, v92, v157, v10
	v_fma_f32 v17, v93, v157, v11
	v_add_f32_dpp v15, v24, v24 row_ror:8 row_mask:0xf bank_mask:0xf bound_ctrl:1
	v_fma_f32 v18, v94, v157, v8
	ds_read_b128 v[124:127], v48 offset:3072
	v_add_f32_dpp v15, v15, v15 row_ror:4 row_mask:0xf bank_mask:0xf bound_ctrl:1
	ds_read_b128 v[128:131], v48 offset:3328
	ds_read_b128 v[132:135], v48 offset:3584
	v_add_f32_dpp v15, v15, v15 row_ror:2 row_mask:0xf bank_mask:0xf bound_ctrl:1
	v_fma_f32 v19, v95, v157, v9
	ds_read_b128 v[136:139], v48 offset:3840
	ds_read_b128 v[160:163], v49 offset:16
	v_add_f32_dpp v30, v15, v15 row_ror:1 row_mask:0xf bank_mask:0xf bound_ctrl:1
	v_pk_fma_f32 v[10:11], v[96:97], v[30:31], v[16:17] op_sel_hi:[1,0,1] neg_lo:[0,1,0] neg_hi:[0,1,0]
	v_pk_fma_f32 v[8:9], v[98:99], v[30:31], v[18:19] op_sel_hi:[1,0,1] neg_lo:[0,1,0] neg_hi:[0,1,0]
	v_pk_mul_f32 v[26:27], v[10:11], v[100:101] op_sel:[0,0] op_sel_hi:[0,1]
	v_pk_fma_f32 v[26:27], v[10:11], v[102:103], v[26:27] op_sel:[1,0,0] op_sel_hi:[1,1,1]
	v_pk_fma_f32 v[26:27], v[8:9], v[104:105], v[26:27] op_sel:[0,0,0] op_sel_hi:[0,1,1]
	v_pk_fma_f32 v[26:27], v[8:9], v[106:107], v[26:27] op_sel:[1,0,0] op_sel_hi:[1,1,1]
	v_fma_f32 v16, v108, v158, v10
	v_fma_f32 v17, v109, v158, v11
	v_add_f32_dpp v15, v26, v26 row_ror:8 row_mask:0xf bank_mask:0xf bound_ctrl:1
	v_fma_f32 v18, v110, v158, v8
	ds_read_b128 v[76:79], v48 offset:4096
	v_add_f32_dpp v15, v15, v15 row_ror:4 row_mask:0xf bank_mask:0xf bound_ctrl:1
	ds_read_b128 v[80:83], v48 offset:4352
	ds_read_b128 v[84:87], v48 offset:4608
	v_add_f32_dpp v15, v15, v15 row_ror:2 row_mask:0xf bank_mask:0xf bound_ctrl:1
	v_fma_f32 v19, v111, v158, v9
	ds_read_b128 v[88:91], v48 offset:4864
	ds_write2st64_b32 v50, v25, v27 offset0:0 offset1:4
	v_add_f32_dpp v30, v15, v15 row_ror:1 row_mask:0xf bank_mask:0xf bound_ctrl:1
	s_waitcnt lgkmcnt(4)
	v_pk_fma_f32 v[10:11], v[112:113], v[30:31], v[16:17] op_sel_hi:[1,0,1] neg_lo:[0,1,0] neg_hi:[0,1,0]
	v_pk_fma_f32 v[8:9], v[114:115], v[30:31], v[18:19] op_sel_hi:[1,0,1] neg_lo:[0,1,0] neg_hi:[0,1,0]
	v_pk_mul_f32 v[24:25], v[10:11], v[116:117] op_sel:[0,0] op_sel_hi:[0,1]
	v_pk_fma_f32 v[24:25], v[10:11], v[118:119], v[24:25] op_sel:[1,0,0] op_sel_hi:[1,1,1]
	v_pk_fma_f32 v[24:25], v[8:9], v[120:121], v[24:25] op_sel:[0,0,0] op_sel_hi:[0,1,1]
	v_pk_fma_f32 v[24:25], v[8:9], v[122:123], v[24:25] op_sel:[1,0,0] op_sel_hi:[1,1,1]
	v_fma_f32 v16, v124, v159, v10
	v_fma_f32 v17, v125, v159, v11
	v_add_f32_dpp v15, v24, v24 row_ror:8 row_mask:0xf bank_mask:0xf bound_ctrl:1
	v_fma_f32 v18, v126, v159, v8
	ds_read_b128 v[92:95], v48 offset:5120
	v_add_f32_dpp v15, v15, v15 row_ror:4 row_mask:0xf bank_mask:0xf bound_ctrl:1
	ds_read_b128 v[96:99], v48 offset:5376
	ds_read_b128 v[100:103], v48 offset:5632
	v_add_f32_dpp v15, v15, v15 row_ror:2 row_mask:0xf bank_mask:0xf bound_ctrl:1
	v_fma_f32 v19, v127, v159, v9
	ds_read_b128 v[104:107], v48 offset:5888
	v_add_f32_dpp v30, v15, v15 row_ror:1 row_mask:0xf bank_mask:0xf bound_ctrl:1
	v_pk_fma_f32 v[10:11], v[128:129], v[30:31], v[16:17] op_sel_hi:[1,0,1] neg_lo:[0,1,0] neg_hi:[0,1,0]
	v_pk_fma_f32 v[8:9], v[130:131], v[30:31], v[18:19] op_sel_hi:[1,0,1] neg_lo:[0,1,0] neg_hi:[0,1,0]
	v_pk_mul_f32 v[26:27], v[10:11], v[132:133] op_sel:[0,0] op_sel_hi:[0,1]
	v_pk_fma_f32 v[26:27], v[10:11], v[134:135], v[26:27] op_sel:[1,0,0] op_sel_hi:[1,1,1]
	v_pk_fma_f32 v[26:27], v[8:9], v[136:137], v[26:27] op_sel:[0,0,0] op_sel_hi:[0,1,1]
	v_pk_fma_f32 v[26:27], v[8:9], v[138:139], v[26:27] op_sel:[1,0,0] op_sel_hi:[1,1,1]
	v_fma_f32 v16, v76, v160, v10
	v_fma_f32 v17, v77, v160, v11
	v_add_f32_dpp v15, v26, v26 row_ror:8 row_mask:0xf bank_mask:0xf bound_ctrl:1
	v_fma_f32 v18, v78, v160, v8
	ds_read_b128 v[108:111], v48 offset:6144
	v_add_f32_dpp v15, v15, v15 row_ror:4 row_mask:0xf bank_mask:0xf bound_ctrl:1
	ds_read_b128 v[112:115], v48 offset:6400
	ds_read_b128 v[116:119], v48 offset:6656
	v_add_f32_dpp v15, v15, v15 row_ror:2 row_mask:0xf bank_mask:0xf bound_ctrl:1
	v_fma_f32 v19, v79, v160, v9
	ds_read_b128 v[120:123], v48 offset:6912
	ds_read_b128 v[140:143], v48 offset:33792
	ds_write2st64_b32 v50, v25, v27 offset0:8 offset1:12
	v_add_f32_dpp v30, v15, v15 row_ror:1 row_mask:0xf bank_mask:0xf bound_ctrl:1
	s_waitcnt lgkmcnt(5)
	v_pk_fma_f32 v[10:11], v[80:81], v[30:31], v[16:17] op_sel_hi:[1,0,1] neg_lo:[0,1,0] neg_hi:[0,1,0]
	v_pk_fma_f32 v[8:9], v[82:83], v[30:31], v[18:19] op_sel_hi:[1,0,1] neg_lo:[0,1,0] neg_hi:[0,1,0]
	v_pk_mul_f32 v[24:25], v[10:11], v[84:85] op_sel:[0,0] op_sel_hi:[0,1]
	v_pk_fma_f32 v[24:25], v[10:11], v[86:87], v[24:25] op_sel:[1,0,0] op_sel_hi:[1,1,1]
	v_pk_fma_f32 v[24:25], v[8:9], v[88:89], v[24:25] op_sel:[0,0,0] op_sel_hi:[0,1,1]
	v_pk_fma_f32 v[24:25], v[8:9], v[90:91], v[24:25] op_sel:[1,0,0] op_sel_hi:[1,1,1]
	v_fma_f32 v16, v92, v161, v10
	v_fma_f32 v17, v93, v161, v11
	v_add_f32_dpp v15, v24, v24 row_ror:8 row_mask:0xf bank_mask:0xf bound_ctrl:1
	v_fma_f32 v18, v94, v161, v8
	ds_read_b128 v[124:127], v48 offset:7168
	v_add_f32_dpp v15, v15, v15 row_ror:4 row_mask:0xf bank_mask:0xf bound_ctrl:1
	ds_read_b128 v[128:131], v48 offset:7424
	ds_read_b128 v[132:135], v48 offset:7680
	v_add_f32_dpp v15, v15, v15 row_ror:2 row_mask:0xf bank_mask:0xf bound_ctrl:1
	v_fma_f32 v19, v95, v161, v9
	ds_read_b128 v[136:139], v48 offset:7936
	ds_read_b128 v[156:159], v49 offset:32
	v_add_f32_dpp v30, v15, v15 row_ror:1 row_mask:0xf bank_mask:0xf bound_ctrl:1
	v_pk_fma_f32 v[10:11], v[96:97], v[30:31], v[16:17] op_sel_hi:[1,0,1] neg_lo:[0,1,0] neg_hi:[0,1,0]
	v_pk_fma_f32 v[8:9], v[98:99], v[30:31], v[18:19] op_sel_hi:[1,0,1] neg_lo:[0,1,0] neg_hi:[0,1,0]
	v_pk_mul_f32 v[26:27], v[10:11], v[100:101] op_sel:[0,0] op_sel_hi:[0,1]
	v_pk_fma_f32 v[26:27], v[10:11], v[102:103], v[26:27] op_sel:[1,0,0] op_sel_hi:[1,1,1]
	v_pk_fma_f32 v[26:27], v[8:9], v[104:105], v[26:27] op_sel:[0,0,0] op_sel_hi:[0,1,1]
	v_pk_fma_f32 v[26:27], v[8:9], v[106:107], v[26:27] op_sel:[1,0,0] op_sel_hi:[1,1,1]
	v_fma_f32 v16, v108, v162, v10
	v_fma_f32 v17, v109, v162, v11
	v_add_f32_dpp v15, v26, v26 row_ror:8 row_mask:0xf bank_mask:0xf bound_ctrl:1
	v_fma_f32 v18, v110, v162, v8
	ds_read_b128 v[76:79], v48 offset:8192
	v_add_f32_dpp v15, v15, v15 row_ror:4 row_mask:0xf bank_mask:0xf bound_ctrl:1
	ds_read_b128 v[80:83], v48 offset:8448
	ds_read_b128 v[84:87], v48 offset:8704
	v_add_f32_dpp v15, v15, v15 row_ror:2 row_mask:0xf bank_mask:0xf bound_ctrl:1
	v_fma_f32 v19, v111, v162, v9
	ds_read_b128 v[88:91], v48 offset:8960
	ds_read_b128 v[144:147], v48 offset:33024
	ds_write2st64_b32 v50, v25, v27 offset0:16 offset1:20
	v_add_f32_dpp v30, v15, v15 row_ror:1 row_mask:0xf bank_mask:0xf bound_ctrl:1
	s_waitcnt lgkmcnt(5)
	v_pk_fma_f32 v[10:11], v[112:113], v[30:31], v[16:17] op_sel_hi:[1,0,1] neg_lo:[0,1,0] neg_hi:[0,1,0]
	v_pk_fma_f32 v[8:9], v[114:115], v[30:31], v[18:19] op_sel_hi:[1,0,1] neg_lo:[0,1,0] neg_hi:[0,1,0]
	v_pk_mul_f32 v[24:25], v[10:11], v[116:117] op_sel:[0,0] op_sel_hi:[0,1]
	v_pk_fma_f32 v[24:25], v[10:11], v[118:119], v[24:25] op_sel:[1,0,0] op_sel_hi:[1,1,1]
	v_pk_fma_f32 v[24:25], v[8:9], v[120:121], v[24:25] op_sel:[0,0,0] op_sel_hi:[0,1,1]
	v_pk_fma_f32 v[24:25], v[8:9], v[122:123], v[24:25] op_sel:[1,0,0] op_sel_hi:[1,1,1]
	v_fma_f32 v16, v124, v163, v10
	v_fma_f32 v17, v125, v163, v11
	v_add_f32_dpp v15, v24, v24 row_ror:8 row_mask:0xf bank_mask:0xf bound_ctrl:1
	v_fma_f32 v18, v126, v163, v8
	ds_read_b128 v[92:95], v48 offset:9216
	v_add_f32_dpp v15, v15, v15 row_ror:4 row_mask:0xf bank_mask:0xf bound_ctrl:1
	ds_read_b128 v[96:99], v48 offset:9472
	ds_read_b128 v[100:103], v48 offset:9728
	v_add_f32_dpp v15, v15, v15 row_ror:2 row_mask:0xf bank_mask:0xf bound_ctrl:1
	v_fma_f32 v19, v127, v163, v9
	ds_read_b128 v[104:107], v48 offset:9984
	v_add_f32_dpp v30, v15, v15 row_ror:1 row_mask:0xf bank_mask:0xf bound_ctrl:1
	v_pk_fma_f32 v[10:11], v[128:129], v[30:31], v[16:17] op_sel_hi:[1,0,1] neg_lo:[0,1,0] neg_hi:[0,1,0]
	v_pk_fma_f32 v[8:9], v[130:131], v[30:31], v[18:19] op_sel_hi:[1,0,1] neg_lo:[0,1,0] neg_hi:[0,1,0]
	v_pk_mul_f32 v[26:27], v[10:11], v[132:133] op_sel:[0,0] op_sel_hi:[0,1]
	v_pk_fma_f32 v[26:27], v[10:11], v[134:135], v[26:27] op_sel:[1,0,0] op_sel_hi:[1,1,1]
	v_pk_fma_f32 v[26:27], v[8:9], v[136:137], v[26:27] op_sel:[0,0,0] op_sel_hi:[0,1,1]
	v_pk_fma_f32 v[26:27], v[8:9], v[138:139], v[26:27] op_sel:[1,0,0] op_sel_hi:[1,1,1]
	ds_write2st64_b32 v50, v25, v27 offset0:24 offset1:28
	v_pk_mul_f32 v[10:11], v[10:11], v[140:141]
	v_pk_mul_f32 v[8:9], v[8:9], v[142:143]
	s_waitcnt lgkmcnt(6)
	v_pk_mul_f32 v[24:25], v[10:11], v[144:145]
	v_pk_fma_f32 v[24:25], v[8:9], v[146:147], v[24:25]
	v_add_f32_e32 v24, v24, v25
	v_fma_f32 v16, v76, v156, v10
	v_fma_f32 v17, v77, v156, v11
	v_add_f32_dpp v15, v24, v24 row_ror:8 row_mask:0xf bank_mask:0xf bound_ctrl:1
	v_fma_f32 v18, v78, v156, v8
	v_fma_f32 v19, v79, v156, v9
	v_add_f32_dpp v15, v15, v15 row_ror:4 row_mask:0xf bank_mask:0xf bound_ctrl:1
	ds_read_b128 v[108:111], v48 offset:10240
	ds_read_b128 v[112:115], v48 offset:10496
	v_add_f32_dpp v15, v15, v15 row_ror:2 row_mask:0xf bank_mask:0xf bound_ctrl:1
	ds_read_b128 v[116:119], v48 offset:10752
	ds_read_b128 v[120:123], v48 offset:11008
	v_add_f32_dpp v30, v15, v15 row_ror:1 row_mask:0xf bank_mask:0xf bound_ctrl:1
	s_waitcnt lgkmcnt(3)
	v_pk_fma_f32 v[10:11], v[80:81], v[30:31], v[16:17] op_sel_hi:[1,0,1] neg_lo:[0,1,0] neg_hi:[0,1,0]
	v_pk_fma_f32 v[8:9], v[82:83], v[30:31], v[18:19] op_sel_hi:[1,0,1] neg_lo:[0,1,0] neg_hi:[0,1,0]
	v_pk_mul_f32 v[24:25], v[10:11], v[84:85] op_sel:[0,0] op_sel_hi:[0,1]
	v_pk_fma_f32 v[24:25], v[10:11], v[86:87], v[24:25] op_sel:[1,0,0] op_sel_hi:[1,1,1]
	v_pk_fma_f32 v[24:25], v[8:9], v[88:89], v[24:25] op_sel:[0,0,0] op_sel_hi:[0,1,1]
	v_pk_fma_f32 v[24:25], v[8:9], v[90:91], v[24:25] op_sel:[1,0,0] op_sel_hi:[1,1,1]
	v_fma_f32 v16, v92, v157, v10
	v_fma_f32 v17, v93, v157, v11
	v_add_f32_dpp v15, v24, v24 row_ror:8 row_mask:0xf bank_mask:0xf bound_ctrl:1
	v_fma_f32 v18, v94, v157, v8
	ds_read_b128 v[124:127], v48 offset:11264
	v_add_f32_dpp v15, v15, v15 row_ror:4 row_mask:0xf bank_mask:0xf bound_ctrl:1
	ds_read_b128 v[128:131], v48 offset:11520
	ds_read_b128 v[132:135], v48 offset:11776
	v_add_f32_dpp v15, v15, v15 row_ror:2 row_mask:0xf bank_mask:0xf bound_ctrl:1
	v_fma_f32 v19, v95, v157, v9
	ds_read_b128 v[136:139], v48 offset:12032
	ds_read_b128 v[160:163], v49 offset:48
	v_add_f32_dpp v30, v15, v15 row_ror:1 row_mask:0xf bank_mask:0xf bound_ctrl:1
	v_pk_fma_f32 v[10:11], v[96:97], v[30:31], v[16:17] op_sel_hi:[1,0,1] neg_lo:[0,1,0] neg_hi:[0,1,0]
	v_pk_fma_f32 v[8:9], v[98:99], v[30:31], v[18:19] op_sel_hi:[1,0,1] neg_lo:[0,1,0] neg_hi:[0,1,0]
	v_pk_mul_f32 v[26:27], v[10:11], v[100:101] op_sel:[0,0] op_sel_hi:[0,1]
	v_pk_fma_f32 v[26:27], v[10:11], v[102:103], v[26:27] op_sel:[1,0,0] op_sel_hi:[1,1,1]
	v_pk_fma_f32 v[26:27], v[8:9], v[104:105], v[26:27] op_sel:[0,0,0] op_sel_hi:[0,1,1]
	v_pk_fma_f32 v[26:27], v[8:9], v[106:107], v[26:27] op_sel:[1,0,0] op_sel_hi:[1,1,1]
	v_fma_f32 v16, v108, v158, v10
	v_fma_f32 v17, v109, v158, v11
	v_add_f32_dpp v15, v26, v26 row_ror:8 row_mask:0xf bank_mask:0xf bound_ctrl:1
	v_fma_f32 v18, v110, v158, v8
	ds_read_b128 v[76:79], v48 offset:12288
	v_add_f32_dpp v15, v15, v15 row_ror:4 row_mask:0xf bank_mask:0xf bound_ctrl:1
	ds_read_b128 v[80:83], v48 offset:12544
	ds_read_b128 v[84:87], v48 offset:12800
	v_add_f32_dpp v15, v15, v15 row_ror:2 row_mask:0xf bank_mask:0xf bound_ctrl:1
	v_fma_f32 v19, v111, v158, v9
	ds_read_b128 v[88:91], v48 offset:13056
	ds_write2st64_b32 v50, v25, v27 offset0:32 offset1:36
	v_add_f32_dpp v30, v15, v15 row_ror:1 row_mask:0xf bank_mask:0xf bound_ctrl:1
	s_waitcnt lgkmcnt(4)
	v_pk_fma_f32 v[10:11], v[112:113], v[30:31], v[16:17] op_sel_hi:[1,0,1] neg_lo:[0,1,0] neg_hi:[0,1,0]
	v_pk_fma_f32 v[8:9], v[114:115], v[30:31], v[18:19] op_sel_hi:[1,0,1] neg_lo:[0,1,0] neg_hi:[0,1,0]
	v_pk_mul_f32 v[24:25], v[10:11], v[116:117] op_sel:[0,0] op_sel_hi:[0,1]
	v_pk_fma_f32 v[24:25], v[10:11], v[118:119], v[24:25] op_sel:[1,0,0] op_sel_hi:[1,1,1]
	v_pk_fma_f32 v[24:25], v[8:9], v[120:121], v[24:25] op_sel:[0,0,0] op_sel_hi:[0,1,1]
	v_pk_fma_f32 v[24:25], v[8:9], v[122:123], v[24:25] op_sel:[1,0,0] op_sel_hi:[1,1,1]
	v_fma_f32 v16, v124, v159, v10
	v_fma_f32 v17, v125, v159, v11
	v_add_f32_dpp v15, v24, v24 row_ror:8 row_mask:0xf bank_mask:0xf bound_ctrl:1
	v_fma_f32 v18, v126, v159, v8
	ds_read_b128 v[92:95], v48 offset:13312
	v_add_f32_dpp v15, v15, v15 row_ror:4 row_mask:0xf bank_mask:0xf bound_ctrl:1
	ds_read_b128 v[96:99], v48 offset:13568
	ds_read_b128 v[100:103], v48 offset:13824
	v_add_f32_dpp v15, v15, v15 row_ror:2 row_mask:0xf bank_mask:0xf bound_ctrl:1
	v_fma_f32 v19, v127, v159, v9
	ds_read_b128 v[104:107], v48 offset:14080
	v_add_f32_dpp v30, v15, v15 row_ror:1 row_mask:0xf bank_mask:0xf bound_ctrl:1
	v_pk_fma_f32 v[10:11], v[128:129], v[30:31], v[16:17] op_sel_hi:[1,0,1] neg_lo:[0,1,0] neg_hi:[0,1,0]
	v_pk_fma_f32 v[8:9], v[130:131], v[30:31], v[18:19] op_sel_hi:[1,0,1] neg_lo:[0,1,0] neg_hi:[0,1,0]
	v_pk_mul_f32 v[26:27], v[10:11], v[132:133] op_sel:[0,0] op_sel_hi:[0,1]
	v_pk_fma_f32 v[26:27], v[10:11], v[134:135], v[26:27] op_sel:[1,0,0] op_sel_hi:[1,1,1]
	v_pk_fma_f32 v[26:27], v[8:9], v[136:137], v[26:27] op_sel:[0,0,0] op_sel_hi:[0,1,1]
	v_pk_fma_f32 v[26:27], v[8:9], v[138:139], v[26:27] op_sel:[1,0,0] op_sel_hi:[1,1,1]
	v_fma_f32 v16, v76, v160, v10
	v_fma_f32 v17, v77, v160, v11
	v_add_f32_dpp v15, v26, v26 row_ror:8 row_mask:0xf bank_mask:0xf bound_ctrl:1
	v_fma_f32 v18, v78, v160, v8
	ds_read_b128 v[108:111], v48 offset:14336
	v_add_f32_dpp v15, v15, v15 row_ror:4 row_mask:0xf bank_mask:0xf bound_ctrl:1
	ds_read_b128 v[112:115], v48 offset:14592
	ds_read_b128 v[116:119], v48 offset:14848
	v_add_f32_dpp v15, v15, v15 row_ror:2 row_mask:0xf bank_mask:0xf bound_ctrl:1
	v_fma_f32 v19, v79, v160, v9
	ds_read_b128 v[120:123], v48 offset:15104
	ds_read_b128 v[140:143], v48 offset:34048
	ds_write2st64_b32 v50, v25, v27 offset0:40 offset1:44
	v_add_f32_dpp v30, v15, v15 row_ror:1 row_mask:0xf bank_mask:0xf bound_ctrl:1
	s_waitcnt lgkmcnt(5)
	v_pk_fma_f32 v[10:11], v[80:81], v[30:31], v[16:17] op_sel_hi:[1,0,1] neg_lo:[0,1,0] neg_hi:[0,1,0]
	v_pk_fma_f32 v[8:9], v[82:83], v[30:31], v[18:19] op_sel_hi:[1,0,1] neg_lo:[0,1,0] neg_hi:[0,1,0]
	v_pk_mul_f32 v[24:25], v[10:11], v[84:85] op_sel:[0,0] op_sel_hi:[0,1]
	v_pk_fma_f32 v[24:25], v[10:11], v[86:87], v[24:25] op_sel:[1,0,0] op_sel_hi:[1,1,1]
	v_pk_fma_f32 v[24:25], v[8:9], v[88:89], v[24:25] op_sel:[0,0,0] op_sel_hi:[0,1,1]
	v_pk_fma_f32 v[24:25], v[8:9], v[90:91], v[24:25] op_sel:[1,0,0] op_sel_hi:[1,1,1]
	v_fma_f32 v16, v92, v161, v10
	v_fma_f32 v17, v93, v161, v11
	v_add_f32_dpp v15, v24, v24 row_ror:8 row_mask:0xf bank_mask:0xf bound_ctrl:1
	v_fma_f32 v18, v94, v161, v8
	ds_read_b128 v[124:127], v48 offset:15360
	v_add_f32_dpp v15, v15, v15 row_ror:4 row_mask:0xf bank_mask:0xf bound_ctrl:1
	ds_read_b128 v[128:131], v48 offset:15616
	ds_read_b128 v[132:135], v48 offset:15872
	v_add_f32_dpp v15, v15, v15 row_ror:2 row_mask:0xf bank_mask:0xf bound_ctrl:1
	v_fma_f32 v19, v95, v161, v9
	ds_read_b128 v[136:139], v48 offset:16128
	ds_read_b128 v[156:159], v49 offset:64
	v_add_f32_dpp v30, v15, v15 row_ror:1 row_mask:0xf bank_mask:0xf bound_ctrl:1
	v_pk_fma_f32 v[10:11], v[96:97], v[30:31], v[16:17] op_sel_hi:[1,0,1] neg_lo:[0,1,0] neg_hi:[0,1,0]
	v_pk_fma_f32 v[8:9], v[98:99], v[30:31], v[18:19] op_sel_hi:[1,0,1] neg_lo:[0,1,0] neg_hi:[0,1,0]
	v_pk_mul_f32 v[26:27], v[10:11], v[100:101] op_sel:[0,0] op_sel_hi:[0,1]
	v_pk_fma_f32 v[26:27], v[10:11], v[102:103], v[26:27] op_sel:[1,0,0] op_sel_hi:[1,1,1]
	v_pk_fma_f32 v[26:27], v[8:9], v[104:105], v[26:27] op_sel:[0,0,0] op_sel_hi:[0,1,1]
	v_pk_fma_f32 v[26:27], v[8:9], v[106:107], v[26:27] op_sel:[1,0,0] op_sel_hi:[1,1,1]
	v_fma_f32 v16, v108, v162, v10
	v_fma_f32 v17, v109, v162, v11
	v_add_f32_dpp v15, v26, v26 row_ror:8 row_mask:0xf bank_mask:0xf bound_ctrl:1
	v_fma_f32 v18, v110, v162, v8
	ds_read_b128 v[76:79], v48 offset:16384
	v_add_f32_dpp v15, v15, v15 row_ror:4 row_mask:0xf bank_mask:0xf bound_ctrl:1
	ds_read_b128 v[80:83], v48 offset:16640
	ds_read_b128 v[84:87], v48 offset:16896
	v_add_f32_dpp v15, v15, v15 row_ror:2 row_mask:0xf bank_mask:0xf bound_ctrl:1
	v_fma_f32 v19, v111, v162, v9
	ds_read_b128 v[88:91], v48 offset:17152
	ds_read_b128 v[144:147], v48 offset:33280
	ds_write2st64_b32 v50, v25, v27 offset0:48 offset1:52
	v_add_f32_dpp v30, v15, v15 row_ror:1 row_mask:0xf bank_mask:0xf bound_ctrl:1
	s_waitcnt lgkmcnt(5)
	v_pk_fma_f32 v[10:11], v[112:113], v[30:31], v[16:17] op_sel_hi:[1,0,1] neg_lo:[0,1,0] neg_hi:[0,1,0]
	v_pk_fma_f32 v[8:9], v[114:115], v[30:31], v[18:19] op_sel_hi:[1,0,1] neg_lo:[0,1,0] neg_hi:[0,1,0]
	v_pk_mul_f32 v[24:25], v[10:11], v[116:117] op_sel:[0,0] op_sel_hi:[0,1]
	v_pk_fma_f32 v[24:25], v[10:11], v[118:119], v[24:25] op_sel:[1,0,0] op_sel_hi:[1,1,1]
	v_pk_fma_f32 v[24:25], v[8:9], v[120:121], v[24:25] op_sel:[0,0,0] op_sel_hi:[0,1,1]
	v_pk_fma_f32 v[24:25], v[8:9], v[122:123], v[24:25] op_sel:[1,0,0] op_sel_hi:[1,1,1]
	v_fma_f32 v16, v124, v163, v10
	v_fma_f32 v17, v125, v163, v11
	v_add_f32_dpp v15, v24, v24 row_ror:8 row_mask:0xf bank_mask:0xf bound_ctrl:1
	v_fma_f32 v18, v126, v163, v8
	ds_read_b128 v[92:95], v48 offset:17408
	v_add_f32_dpp v15, v15, v15 row_ror:4 row_mask:0xf bank_mask:0xf bound_ctrl:1
	ds_read_b128 v[96:99], v48 offset:17664
	ds_read_b128 v[100:103], v48 offset:17920
	v_add_f32_dpp v15, v15, v15 row_ror:2 row_mask:0xf bank_mask:0xf bound_ctrl:1
	v_fma_f32 v19, v127, v163, v9
	ds_read_b128 v[104:107], v48 offset:18176
	v_add_f32_dpp v30, v15, v15 row_ror:1 row_mask:0xf bank_mask:0xf bound_ctrl:1
	v_pk_fma_f32 v[10:11], v[128:129], v[30:31], v[16:17] op_sel_hi:[1,0,1] neg_lo:[0,1,0] neg_hi:[0,1,0]
	v_pk_fma_f32 v[8:9], v[130:131], v[30:31], v[18:19] op_sel_hi:[1,0,1] neg_lo:[0,1,0] neg_hi:[0,1,0]
	v_pk_mul_f32 v[26:27], v[10:11], v[132:133] op_sel:[0,0] op_sel_hi:[0,1]
	v_pk_fma_f32 v[26:27], v[10:11], v[134:135], v[26:27] op_sel:[1,0,0] op_sel_hi:[1,1,1]
	v_pk_fma_f32 v[26:27], v[8:9], v[136:137], v[26:27] op_sel:[0,0,0] op_sel_hi:[0,1,1]
	v_pk_fma_f32 v[26:27], v[8:9], v[138:139], v[26:27] op_sel:[1,0,0] op_sel_hi:[1,1,1]
	ds_write2st64_b32 v50, v25, v27 offset0:56 offset1:60
	v_pk_mul_f32 v[10:11], v[10:11], v[140:141]
	v_pk_mul_f32 v[8:9], v[8:9], v[142:143]
	s_waitcnt lgkmcnt(6)
	v_pk_mul_f32 v[24:25], v[10:11], v[144:145]
	v_pk_fma_f32 v[24:25], v[8:9], v[146:147], v[24:25]
	v_add_f32_e32 v24, v24, v25
	v_fma_f32 v16, v76, v156, v10
	v_fma_f32 v17, v77, v156, v11
	v_add_f32_dpp v15, v24, v24 row_ror:8 row_mask:0xf bank_mask:0xf bound_ctrl:1
	v_fma_f32 v18, v78, v156, v8
	v_fma_f32 v19, v79, v156, v9
	v_add_f32_dpp v15, v15, v15 row_ror:4 row_mask:0xf bank_mask:0xf bound_ctrl:1
	ds_read_b128 v[108:111], v48 offset:18432
	ds_read_b128 v[112:115], v48 offset:18688
	v_add_f32_dpp v15, v15, v15 row_ror:2 row_mask:0xf bank_mask:0xf bound_ctrl:1
	ds_read_b128 v[116:119], v48 offset:18944
	ds_read_b128 v[120:123], v48 offset:19200
	v_add_f32_dpp v30, v15, v15 row_ror:1 row_mask:0xf bank_mask:0xf bound_ctrl:1
	s_waitcnt lgkmcnt(3)
	v_pk_fma_f32 v[10:11], v[80:81], v[30:31], v[16:17] op_sel_hi:[1,0,1] neg_lo:[0,1,0] neg_hi:[0,1,0]
	v_pk_fma_f32 v[8:9], v[82:83], v[30:31], v[18:19] op_sel_hi:[1,0,1] neg_lo:[0,1,0] neg_hi:[0,1,0]
	v_pk_mul_f32 v[24:25], v[10:11], v[84:85] op_sel:[0,0] op_sel_hi:[0,1]
	v_pk_fma_f32 v[24:25], v[10:11], v[86:87], v[24:25] op_sel:[1,0,0] op_sel_hi:[1,1,1]
	v_pk_fma_f32 v[24:25], v[8:9], v[88:89], v[24:25] op_sel:[0,0,0] op_sel_hi:[0,1,1]
	v_pk_fma_f32 v[24:25], v[8:9], v[90:91], v[24:25] op_sel:[1,0,0] op_sel_hi:[1,1,1]
	v_fma_f32 v16, v92, v157, v10
	v_fma_f32 v17, v93, v157, v11
	v_add_f32_dpp v15, v24, v24 row_ror:8 row_mask:0xf bank_mask:0xf bound_ctrl:1
	v_fma_f32 v18, v94, v157, v8
	ds_read_b128 v[124:127], v48 offset:19456
	v_add_f32_dpp v15, v15, v15 row_ror:4 row_mask:0xf bank_mask:0xf bound_ctrl:1
	ds_read_b128 v[128:131], v48 offset:19712
	ds_read_b128 v[132:135], v48 offset:19968
	v_add_f32_dpp v15, v15, v15 row_ror:2 row_mask:0xf bank_mask:0xf bound_ctrl:1
	v_fma_f32 v19, v95, v157, v9
	ds_read_b128 v[136:139], v48 offset:20224
	ds_read_b128 v[160:163], v49 offset:80
	v_add_f32_dpp v30, v15, v15 row_ror:1 row_mask:0xf bank_mask:0xf bound_ctrl:1
	v_pk_fma_f32 v[10:11], v[96:97], v[30:31], v[16:17] op_sel_hi:[1,0,1] neg_lo:[0,1,0] neg_hi:[0,1,0]
	v_pk_fma_f32 v[8:9], v[98:99], v[30:31], v[18:19] op_sel_hi:[1,0,1] neg_lo:[0,1,0] neg_hi:[0,1,0]
	v_pk_mul_f32 v[26:27], v[10:11], v[100:101] op_sel:[0,0] op_sel_hi:[0,1]
	v_pk_fma_f32 v[26:27], v[10:11], v[102:103], v[26:27] op_sel:[1,0,0] op_sel_hi:[1,1,1]
	v_pk_fma_f32 v[26:27], v[8:9], v[104:105], v[26:27] op_sel:[0,0,0] op_sel_hi:[0,1,1]
	v_pk_fma_f32 v[26:27], v[8:9], v[106:107], v[26:27] op_sel:[1,0,0] op_sel_hi:[1,1,1]
	v_fma_f32 v16, v108, v158, v10
	v_fma_f32 v17, v109, v158, v11
	v_add_f32_dpp v15, v26, v26 row_ror:8 row_mask:0xf bank_mask:0xf bound_ctrl:1
	v_fma_f32 v18, v110, v158, v8
	ds_read_b128 v[76:79], v48 offset:20480
	v_add_f32_dpp v15, v15, v15 row_ror:4 row_mask:0xf bank_mask:0xf bound_ctrl:1
	ds_read_b128 v[80:83], v48 offset:20736
	ds_read_b128 v[84:87], v48 offset:20992
	v_add_f32_dpp v15, v15, v15 row_ror:2 row_mask:0xf bank_mask:0xf bound_ctrl:1
	v_fma_f32 v19, v111, v158, v9
	ds_read_b128 v[88:91], v48 offset:21248
	ds_write2st64_b32 v50, v25, v27 offset0:64 offset1:68
	v_add_f32_dpp v30, v15, v15 row_ror:1 row_mask:0xf bank_mask:0xf bound_ctrl:1
	s_waitcnt lgkmcnt(4)
	v_pk_fma_f32 v[10:11], v[112:113], v[30:31], v[16:17] op_sel_hi:[1,0,1] neg_lo:[0,1,0] neg_hi:[0,1,0]
	v_pk_fma_f32 v[8:9], v[114:115], v[30:31], v[18:19] op_sel_hi:[1,0,1] neg_lo:[0,1,0] neg_hi:[0,1,0]
	v_pk_mul_f32 v[24:25], v[10:11], v[116:117] op_sel:[0,0] op_sel_hi:[0,1]
	v_pk_fma_f32 v[24:25], v[10:11], v[118:119], v[24:25] op_sel:[1,0,0] op_sel_hi:[1,1,1]
	v_pk_fma_f32 v[24:25], v[8:9], v[120:121], v[24:25] op_sel:[0,0,0] op_sel_hi:[0,1,1]
	v_pk_fma_f32 v[24:25], v[8:9], v[122:123], v[24:25] op_sel:[1,0,0] op_sel_hi:[1,1,1]
	v_fma_f32 v16, v124, v159, v10
	v_fma_f32 v17, v125, v159, v11
	v_add_f32_dpp v15, v24, v24 row_ror:8 row_mask:0xf bank_mask:0xf bound_ctrl:1
	v_fma_f32 v18, v126, v159, v8
	ds_read_b128 v[92:95], v48 offset:21504
	v_add_f32_dpp v15, v15, v15 row_ror:4 row_mask:0xf bank_mask:0xf bound_ctrl:1
	ds_read_b128 v[96:99], v48 offset:21760
	ds_read_b128 v[100:103], v48 offset:22016
	v_add_f32_dpp v15, v15, v15 row_ror:2 row_mask:0xf bank_mask:0xf bound_ctrl:1
	v_fma_f32 v19, v127, v159, v9
	ds_read_b128 v[104:107], v48 offset:22272
	v_add_f32_dpp v30, v15, v15 row_ror:1 row_mask:0xf bank_mask:0xf bound_ctrl:1
	v_pk_fma_f32 v[10:11], v[128:129], v[30:31], v[16:17] op_sel_hi:[1,0,1] neg_lo:[0,1,0] neg_hi:[0,1,0]
	v_pk_fma_f32 v[8:9], v[130:131], v[30:31], v[18:19] op_sel_hi:[1,0,1] neg_lo:[0,1,0] neg_hi:[0,1,0]
	v_pk_mul_f32 v[26:27], v[10:11], v[132:133] op_sel:[0,0] op_sel_hi:[0,1]
	v_pk_fma_f32 v[26:27], v[10:11], v[134:135], v[26:27] op_sel:[1,0,0] op_sel_hi:[1,1,1]
	v_pk_fma_f32 v[26:27], v[8:9], v[136:137], v[26:27] op_sel:[0,0,0] op_sel_hi:[0,1,1]
	v_pk_fma_f32 v[26:27], v[8:9], v[138:139], v[26:27] op_sel:[1,0,0] op_sel_hi:[1,1,1]
	v_fma_f32 v16, v76, v160, v10
	v_fma_f32 v17, v77, v160, v11
	v_add_f32_dpp v15, v26, v26 row_ror:8 row_mask:0xf bank_mask:0xf bound_ctrl:1
	v_fma_f32 v18, v78, v160, v8
	ds_read_b128 v[108:111], v48 offset:22528
	v_add_f32_dpp v15, v15, v15 row_ror:4 row_mask:0xf bank_mask:0xf bound_ctrl:1
	ds_read_b128 v[112:115], v48 offset:22784
	ds_read_b128 v[116:119], v48 offset:23040
	v_add_f32_dpp v15, v15, v15 row_ror:2 row_mask:0xf bank_mask:0xf bound_ctrl:1
	v_fma_f32 v19, v79, v160, v9
	ds_read_b128 v[120:123], v48 offset:23296
	ds_read_b128 v[140:143], v48 offset:34304
	ds_write2st64_b32 v50, v25, v27 offset0:72 offset1:76
	v_add_f32_dpp v30, v15, v15 row_ror:1 row_mask:0xf bank_mask:0xf bound_ctrl:1
	s_waitcnt lgkmcnt(5)
	v_pk_fma_f32 v[10:11], v[80:81], v[30:31], v[16:17] op_sel_hi:[1,0,1] neg_lo:[0,1,0] neg_hi:[0,1,0]
	v_pk_fma_f32 v[8:9], v[82:83], v[30:31], v[18:19] op_sel_hi:[1,0,1] neg_lo:[0,1,0] neg_hi:[0,1,0]
	v_pk_mul_f32 v[24:25], v[10:11], v[84:85] op_sel:[0,0] op_sel_hi:[0,1]
	v_pk_fma_f32 v[24:25], v[10:11], v[86:87], v[24:25] op_sel:[1,0,0] op_sel_hi:[1,1,1]
	v_pk_fma_f32 v[24:25], v[8:9], v[88:89], v[24:25] op_sel:[0,0,0] op_sel_hi:[0,1,1]
	v_pk_fma_f32 v[24:25], v[8:9], v[90:91], v[24:25] op_sel:[1,0,0] op_sel_hi:[1,1,1]
	v_fma_f32 v16, v92, v161, v10
	v_fma_f32 v17, v93, v161, v11
	v_add_f32_dpp v15, v24, v24 row_ror:8 row_mask:0xf bank_mask:0xf bound_ctrl:1
	v_fma_f32 v18, v94, v161, v8
	ds_read_b128 v[124:127], v48 offset:23552
	v_add_f32_dpp v15, v15, v15 row_ror:4 row_mask:0xf bank_mask:0xf bound_ctrl:1
	ds_read_b128 v[128:131], v48 offset:23808
	ds_read_b128 v[132:135], v48 offset:24064
	v_add_f32_dpp v15, v15, v15 row_ror:2 row_mask:0xf bank_mask:0xf bound_ctrl:1
	v_fma_f32 v19, v95, v161, v9
	ds_read_b128 v[136:139], v48 offset:24320
	ds_read_b128 v[156:159], v49 offset:96
	v_add_f32_dpp v30, v15, v15 row_ror:1 row_mask:0xf bank_mask:0xf bound_ctrl:1
	v_pk_fma_f32 v[10:11], v[96:97], v[30:31], v[16:17] op_sel_hi:[1,0,1] neg_lo:[0,1,0] neg_hi:[0,1,0]
	v_pk_fma_f32 v[8:9], v[98:99], v[30:31], v[18:19] op_sel_hi:[1,0,1] neg_lo:[0,1,0] neg_hi:[0,1,0]
	v_pk_mul_f32 v[26:27], v[10:11], v[100:101] op_sel:[0,0] op_sel_hi:[0,1]
	v_pk_fma_f32 v[26:27], v[10:11], v[102:103], v[26:27] op_sel:[1,0,0] op_sel_hi:[1,1,1]
	v_pk_fma_f32 v[26:27], v[8:9], v[104:105], v[26:27] op_sel:[0,0,0] op_sel_hi:[0,1,1]
	v_pk_fma_f32 v[26:27], v[8:9], v[106:107], v[26:27] op_sel:[1,0,0] op_sel_hi:[1,1,1]
	v_fma_f32 v16, v108, v162, v10
	v_fma_f32 v17, v109, v162, v11
	v_add_f32_dpp v15, v26, v26 row_ror:8 row_mask:0xf bank_mask:0xf bound_ctrl:1
	v_fma_f32 v18, v110, v162, v8
	ds_read_b128 v[76:79], v48 offset:24576
	v_add_f32_dpp v15, v15, v15 row_ror:4 row_mask:0xf bank_mask:0xf bound_ctrl:1
	ds_read_b128 v[80:83], v48 offset:24832
	ds_read_b128 v[84:87], v48 offset:25088
	v_add_f32_dpp v15, v15, v15 row_ror:2 row_mask:0xf bank_mask:0xf bound_ctrl:1
	v_fma_f32 v19, v111, v162, v9
	ds_read_b128 v[88:91], v48 offset:25344
	ds_read_b128 v[144:147], v48 offset:33536
	ds_write2st64_b32 v50, v25, v27 offset0:80 offset1:84
	v_add_f32_dpp v30, v15, v15 row_ror:1 row_mask:0xf bank_mask:0xf bound_ctrl:1
	s_waitcnt lgkmcnt(5)
	v_pk_fma_f32 v[10:11], v[112:113], v[30:31], v[16:17] op_sel_hi:[1,0,1] neg_lo:[0,1,0] neg_hi:[0,1,0]
	v_pk_fma_f32 v[8:9], v[114:115], v[30:31], v[18:19] op_sel_hi:[1,0,1] neg_lo:[0,1,0] neg_hi:[0,1,0]
	v_pk_mul_f32 v[24:25], v[10:11], v[116:117] op_sel:[0,0] op_sel_hi:[0,1]
	v_pk_fma_f32 v[24:25], v[10:11], v[118:119], v[24:25] op_sel:[1,0,0] op_sel_hi:[1,1,1]
	v_pk_fma_f32 v[24:25], v[8:9], v[120:121], v[24:25] op_sel:[0,0,0] op_sel_hi:[0,1,1]
	v_pk_fma_f32 v[24:25], v[8:9], v[122:123], v[24:25] op_sel:[1,0,0] op_sel_hi:[1,1,1]
	v_fma_f32 v16, v124, v163, v10
	v_fma_f32 v17, v125, v163, v11
	v_add_f32_dpp v15, v24, v24 row_ror:8 row_mask:0xf bank_mask:0xf bound_ctrl:1
	v_fma_f32 v18, v126, v163, v8
	ds_read_b128 v[92:95], v48 offset:25600
	v_add_f32_dpp v15, v15, v15 row_ror:4 row_mask:0xf bank_mask:0xf bound_ctrl:1
	ds_read_b128 v[96:99], v48 offset:25856
	ds_read_b128 v[100:103], v48 offset:26112
	v_add_f32_dpp v15, v15, v15 row_ror:2 row_mask:0xf bank_mask:0xf bound_ctrl:1
	v_fma_f32 v19, v127, v163, v9
	ds_read_b128 v[104:107], v48 offset:26368
	v_add_f32_dpp v30, v15, v15 row_ror:1 row_mask:0xf bank_mask:0xf bound_ctrl:1
	v_pk_fma_f32 v[10:11], v[128:129], v[30:31], v[16:17] op_sel_hi:[1,0,1] neg_lo:[0,1,0] neg_hi:[0,1,0]
	v_pk_fma_f32 v[8:9], v[130:131], v[30:31], v[18:19] op_sel_hi:[1,0,1] neg_lo:[0,1,0] neg_hi:[0,1,0]
	v_pk_mul_f32 v[26:27], v[10:11], v[132:133] op_sel:[0,0] op_sel_hi:[0,1]
	v_pk_fma_f32 v[26:27], v[10:11], v[134:135], v[26:27] op_sel:[1,0,0] op_sel_hi:[1,1,1]
	v_pk_fma_f32 v[26:27], v[8:9], v[136:137], v[26:27] op_sel:[0,0,0] op_sel_hi:[0,1,1]
	v_pk_fma_f32 v[26:27], v[8:9], v[138:139], v[26:27] op_sel:[1,0,0] op_sel_hi:[1,1,1]
	ds_write2st64_b32 v50, v25, v27 offset0:88 offset1:92
	v_pk_mul_f32 v[10:11], v[10:11], v[140:141]
	v_pk_mul_f32 v[8:9], v[8:9], v[142:143]
	s_waitcnt lgkmcnt(6)
	v_pk_mul_f32 v[24:25], v[10:11], v[144:145]
	v_pk_fma_f32 v[24:25], v[8:9], v[146:147], v[24:25]
	v_add_f32_e32 v24, v24, v25
	v_fma_f32 v16, v76, v156, v10
	v_fma_f32 v17, v77, v156, v11
	v_add_f32_dpp v15, v24, v24 row_ror:8 row_mask:0xf bank_mask:0xf bound_ctrl:1
	v_fma_f32 v18, v78, v156, v8
	v_fma_f32 v19, v79, v156, v9
	v_add_f32_dpp v15, v15, v15 row_ror:4 row_mask:0xf bank_mask:0xf bound_ctrl:1
	ds_read_b128 v[108:111], v48 offset:26624
	ds_read_b128 v[112:115], v48 offset:26880
	v_add_f32_dpp v15, v15, v15 row_ror:2 row_mask:0xf bank_mask:0xf bound_ctrl:1
	ds_read_b128 v[116:119], v48 offset:27136
	ds_read_b128 v[120:123], v48 offset:27392
	v_add_f32_dpp v30, v15, v15 row_ror:1 row_mask:0xf bank_mask:0xf bound_ctrl:1
	s_waitcnt lgkmcnt(3)
	v_pk_fma_f32 v[10:11], v[80:81], v[30:31], v[16:17] op_sel_hi:[1,0,1] neg_lo:[0,1,0] neg_hi:[0,1,0]
	v_pk_fma_f32 v[8:9], v[82:83], v[30:31], v[18:19] op_sel_hi:[1,0,1] neg_lo:[0,1,0] neg_hi:[0,1,0]
	v_pk_mul_f32 v[24:25], v[10:11], v[84:85] op_sel:[0,0] op_sel_hi:[0,1]
	v_pk_fma_f32 v[24:25], v[10:11], v[86:87], v[24:25] op_sel:[1,0,0] op_sel_hi:[1,1,1]
	v_pk_fma_f32 v[24:25], v[8:9], v[88:89], v[24:25] op_sel:[0,0,0] op_sel_hi:[0,1,1]
	v_pk_fma_f32 v[24:25], v[8:9], v[90:91], v[24:25] op_sel:[1,0,0] op_sel_hi:[1,1,1]
	v_fma_f32 v16, v92, v157, v10
	v_fma_f32 v17, v93, v157, v11
	v_add_f32_dpp v15, v24, v24 row_ror:8 row_mask:0xf bank_mask:0xf bound_ctrl:1
	v_fma_f32 v18, v94, v157, v8
	ds_read_b128 v[124:127], v48 offset:27648
	v_add_f32_dpp v15, v15, v15 row_ror:4 row_mask:0xf bank_mask:0xf bound_ctrl:1
	ds_read_b128 v[128:131], v48 offset:27904
	ds_read_b128 v[132:135], v48 offset:28160
	v_add_f32_dpp v15, v15, v15 row_ror:2 row_mask:0xf bank_mask:0xf bound_ctrl:1
	v_fma_f32 v19, v95, v157, v9
	ds_read_b128 v[136:139], v48 offset:28416
	ds_read_b128 v[160:163], v49 offset:112
	v_add_f32_dpp v30, v15, v15 row_ror:1 row_mask:0xf bank_mask:0xf bound_ctrl:1
	v_pk_fma_f32 v[10:11], v[96:97], v[30:31], v[16:17] op_sel_hi:[1,0,1] neg_lo:[0,1,0] neg_hi:[0,1,0]
	v_pk_fma_f32 v[8:9], v[98:99], v[30:31], v[18:19] op_sel_hi:[1,0,1] neg_lo:[0,1,0] neg_hi:[0,1,0]
	v_pk_mul_f32 v[26:27], v[10:11], v[100:101] op_sel:[0,0] op_sel_hi:[0,1]
	v_pk_fma_f32 v[26:27], v[10:11], v[102:103], v[26:27] op_sel:[1,0,0] op_sel_hi:[1,1,1]
	v_pk_fma_f32 v[26:27], v[8:9], v[104:105], v[26:27] op_sel:[0,0,0] op_sel_hi:[0,1,1]
	v_pk_fma_f32 v[26:27], v[8:9], v[106:107], v[26:27] op_sel:[1,0,0] op_sel_hi:[1,1,1]
	v_fma_f32 v16, v108, v158, v10
	v_fma_f32 v17, v109, v158, v11
	v_add_f32_dpp v15, v26, v26 row_ror:8 row_mask:0xf bank_mask:0xf bound_ctrl:1
	v_fma_f32 v18, v110, v158, v8
	ds_read_b128 v[76:79], v48 offset:28672
	v_add_f32_dpp v15, v15, v15 row_ror:4 row_mask:0xf bank_mask:0xf bound_ctrl:1
	ds_read_b128 v[80:83], v48 offset:28928
	ds_read_b128 v[84:87], v48 offset:29184
	v_add_f32_dpp v15, v15, v15 row_ror:2 row_mask:0xf bank_mask:0xf bound_ctrl:1
	v_fma_f32 v19, v111, v158, v9
	ds_read_b128 v[88:91], v48 offset:29440
	ds_write2st64_b32 v50, v25, v27 offset0:96 offset1:100
	v_add_f32_dpp v30, v15, v15 row_ror:1 row_mask:0xf bank_mask:0xf bound_ctrl:1
	ds_read_b128 v[56:59], v52
	s_waitcnt lgkmcnt(5)
	v_pk_fma_f32 v[10:11], v[112:113], v[30:31], v[16:17] op_sel_hi:[1,0,1] neg_lo:[0,1,0] neg_hi:[0,1,0]
	v_pk_fma_f32 v[8:9], v[114:115], v[30:31], v[18:19] op_sel_hi:[1,0,1] neg_lo:[0,1,0] neg_hi:[0,1,0]
	v_pk_mul_f32 v[24:25], v[10:11], v[116:117] op_sel:[0,0] op_sel_hi:[0,1]
	v_pk_fma_f32 v[24:25], v[10:11], v[118:119], v[24:25] op_sel:[1,0,0] op_sel_hi:[1,1,1]
	v_pk_fma_f32 v[24:25], v[8:9], v[120:121], v[24:25] op_sel:[0,0,0] op_sel_hi:[0,1,1]
	v_pk_fma_f32 v[24:25], v[8:9], v[122:123], v[24:25] op_sel:[1,0,0] op_sel_hi:[1,1,1]
	v_fma_f32 v16, v124, v159, v10
	v_fma_f32 v17, v125, v159, v11
	v_add_f32_dpp v15, v24, v24 row_ror:8 row_mask:0xf bank_mask:0xf bound_ctrl:1
	v_fma_f32 v18, v126, v159, v8
	ds_read_b128 v[92:95], v48 offset:29696
	v_add_f32_dpp v15, v15, v15 row_ror:4 row_mask:0xf bank_mask:0xf bound_ctrl:1
	ds_read_b128 v[96:99], v48 offset:29952
	ds_read_b128 v[100:103], v48 offset:30208
	v_add_f32_dpp v15, v15, v15 row_ror:2 row_mask:0xf bank_mask:0xf bound_ctrl:1
	v_fma_f32 v19, v127, v159, v9
	ds_read_b128 v[104:107], v48 offset:30464
	v_add_f32_dpp v30, v15, v15 row_ror:1 row_mask:0xf bank_mask:0xf bound_ctrl:1
	s_waitcnt lgkmcnt(4)
	v_min_u32_e32 v56, v56, v57
	v_min3_u32 v56, v56, v58, v59
	v_pk_fma_f32 v[10:11], v[128:129], v[30:31], v[16:17] op_sel_hi:[1,0,1] neg_lo:[0,1,0] neg_hi:[0,1,0]
	v_pk_fma_f32 v[8:9], v[130:131], v[30:31], v[18:19] op_sel_hi:[1,0,1] neg_lo:[0,1,0] neg_hi:[0,1,0]
	v_pk_mul_f32 v[26:27], v[10:11], v[132:133] op_sel:[0,0] op_sel_hi:[0,1]
	v_pk_fma_f32 v[26:27], v[10:11], v[134:135], v[26:27] op_sel:[1,0,0] op_sel_hi:[1,1,1]
	v_pk_fma_f32 v[26:27], v[8:9], v[136:137], v[26:27] op_sel:[0,0,0] op_sel_hi:[0,1,1]
	v_pk_fma_f32 v[26:27], v[8:9], v[138:139], v[26:27] op_sel:[1,0,0] op_sel_hi:[1,1,1]
	v_fma_f32 v16, v76, v160, v10
	v_fma_f32 v17, v77, v160, v11
	v_add_f32_dpp v15, v26, v26 row_ror:8 row_mask:0xf bank_mask:0xf bound_ctrl:1
	v_fma_f32 v18, v78, v160, v8
	ds_read_b128 v[108:111], v48 offset:30720
	v_add_f32_dpp v15, v15, v15 row_ror:4 row_mask:0xf bank_mask:0xf bound_ctrl:1
	ds_read_b128 v[112:115], v48 offset:30976
	ds_read_b128 v[116:119], v48 offset:31232
	v_add_f32_dpp v15, v15, v15 row_ror:2 row_mask:0xf bank_mask:0xf bound_ctrl:1
	v_fma_f32 v19, v79, v160, v9
	ds_read_b128 v[120:123], v48 offset:31488
	ds_read_b128 v[140:143], v48 offset:34560
	ds_write2st64_b32 v50, v25, v27 offset0:104 offset1:108
	v_add_f32_dpp v30, v15, v15 row_ror:1 row_mask:0xf bank_mask:0xf bound_ctrl:1
	s_waitcnt lgkmcnt(5)
	v_pk_fma_f32 v[10:11], v[80:81], v[30:31], v[16:17] op_sel_hi:[1,0,1] neg_lo:[0,1,0] neg_hi:[0,1,0]
	v_pk_fma_f32 v[8:9], v[82:83], v[30:31], v[18:19] op_sel_hi:[1,0,1] neg_lo:[0,1,0] neg_hi:[0,1,0]
	v_pk_mul_f32 v[24:25], v[10:11], v[84:85] op_sel:[0,0] op_sel_hi:[0,1]
	v_pk_fma_f32 v[24:25], v[10:11], v[86:87], v[24:25] op_sel:[1,0,0] op_sel_hi:[1,1,1]
	v_pk_fma_f32 v[24:25], v[8:9], v[88:89], v[24:25] op_sel:[0,0,0] op_sel_hi:[0,1,1]
	v_pk_fma_f32 v[24:25], v[8:9], v[90:91], v[24:25] op_sel:[1,0,0] op_sel_hi:[1,1,1]
	v_fma_f32 v16, v92, v161, v10
	v_fma_f32 v17, v93, v161, v11
	v_add_f32_dpp v15, v24, v24 row_ror:8 row_mask:0xf bank_mask:0xf bound_ctrl:1
	v_fma_f32 v18, v94, v161, v8
	ds_read_b128 v[124:127], v48 offset:31744
	v_add_f32_dpp v15, v15, v15 row_ror:4 row_mask:0xf bank_mask:0xf bound_ctrl:1
	ds_read_b128 v[128:131], v48 offset:32000
	ds_read_b128 v[132:135], v48 offset:32256
	v_add_f32_dpp v15, v15, v15 row_ror:2 row_mask:0xf bank_mask:0xf bound_ctrl:1
	v_fma_f32 v19, v95, v161, v9
	ds_read_b128 v[136:139], v48 offset:32512
	v_add_f32_dpp v30, v15, v15 row_ror:1 row_mask:0xf bank_mask:0xf bound_ctrl:1
	v_readfirstlane_b32 s54, v56
	s_add_u32 s64, s6, 2
	s_cmp_lt_u32 s54, s64
	s_cbranch_scc1 .Lss_spin_1
.Lss_ok_1:
	v_pk_fma_f32 v[10:11], v[96:97], v[30:31], v[16:17] op_sel_hi:[1,0,1] neg_lo:[0,1,0] neg_hi:[0,1,0]
	v_pk_fma_f32 v[8:9], v[98:99], v[30:31], v[18:19] op_sel_hi:[1,0,1] neg_lo:[0,1,0] neg_hi:[0,1,0]
	v_pk_mul_f32 v[26:27], v[10:11], v[100:101] op_sel:[0,0] op_sel_hi:[0,1]
	v_pk_fma_f32 v[26:27], v[10:11], v[102:103], v[26:27] op_sel:[1,0,0] op_sel_hi:[1,1,1]
	v_pk_fma_f32 v[26:27], v[8:9], v[104:105], v[26:27] op_sel:[0,0,0] op_sel_hi:[0,1,1]
	v_pk_fma_f32 v[26:27], v[8:9], v[106:107], v[26:27] op_sel:[1,0,0] op_sel_hi:[1,1,1]
	v_fma_f32 v16, v108, v162, v10
	v_fma_f32 v17, v109, v162, v11
	v_add_f32_dpp v15, v26, v26 row_ror:8 row_mask:0xf bank_mask:0xf bound_ctrl:1
	v_fma_f32 v18, v110, v162, v8
	ds_read_b128 v[76:79], v34 offset:0
	v_add_f32_dpp v15, v15, v15 row_ror:4 row_mask:0xf bank_mask:0xf bound_ctrl:1
	ds_read_b128 v[80:83], v34 offset:256
	ds_read_b128 v[84:87], v34 offset:512
	v_add_f32_dpp v15, v15, v15 row_ror:2 row_mask:0xf bank_mask:0xf bound_ctrl:1
	v_fma_f32 v19, v111, v162, v9
	ds_read_b128 v[88:91], v34 offset:768
	ds_read_b128 v[144:147], v34 offset:32768
	ds_write2st64_b32 v50, v25, v27 offset0:112 offset1:116
	v_add_f32_dpp v30, v15, v15 row_ror:1 row_mask:0xf bank_mask:0xf bound_ctrl:1
	ds_read_b128 v[156:159], v35 offset:0
	s_waitcnt lgkmcnt(6)
	v_pk_fma_f32 v[10:11], v[112:113], v[30:31], v[16:17] op_sel_hi:[1,0,1] neg_lo:[0,1,0] neg_hi:[0,1,0]
	v_pk_fma_f32 v[8:9], v[114:115], v[30:31], v[18:19] op_sel_hi:[1,0,1] neg_lo:[0,1,0] neg_hi:[0,1,0]
	v_pk_mul_f32 v[24:25], v[10:11], v[116:117] op_sel:[0,0] op_sel_hi:[0,1]
	v_pk_fma_f32 v[24:25], v[10:11], v[118:119], v[24:25] op_sel:[1,0,0] op_sel_hi:[1,1,1]
	v_pk_fma_f32 v[24:25], v[8:9], v[120:121], v[24:25] op_sel:[0,0,0] op_sel_hi:[0,1,1]
	v_pk_fma_f32 v[24:25], v[8:9], v[122:123], v[24:25] op_sel:[1,0,0] op_sel_hi:[1,1,1]
	v_fma_f32 v16, v124, v163, v10
	v_fma_f32 v17, v125, v163, v11
	v_add_f32_dpp v15, v24, v24 row_ror:8 row_mask:0xf bank_mask:0xf bound_ctrl:1
	v_fma_f32 v18, v126, v163, v8
	ds_read_b128 v[92:95], v34 offset:1024
	v_add_f32_dpp v15, v15, v15 row_ror:4 row_mask:0xf bank_mask:0xf bound_ctrl:1
	ds_read_b128 v[96:99], v34 offset:1280
	ds_read_b128 v[100:103], v34 offset:1536
	v_add_f32_dpp v15, v15, v15 row_ror:2 row_mask:0xf bank_mask:0xf bound_ctrl:1
	v_fma_f32 v19, v127, v163, v9
	ds_read_b128 v[104:107], v34 offset:1792
	v_add_f32_dpp v30, v15, v15 row_ror:1 row_mask:0xf bank_mask:0xf bound_ctrl:1
	v_pk_fma_f32 v[10:11], v[128:129], v[30:31], v[16:17] op_sel_hi:[1,0,1] neg_lo:[0,1,0] neg_hi:[0,1,0]
	v_pk_fma_f32 v[8:9], v[130:131], v[30:31], v[18:19] op_sel_hi:[1,0,1] neg_lo:[0,1,0] neg_hi:[0,1,0]
	v_pk_mul_f32 v[26:27], v[10:11], v[132:133] op_sel:[0,0] op_sel_hi:[0,1]
	v_pk_fma_f32 v[26:27], v[10:11], v[134:135], v[26:27] op_sel:[1,0,0] op_sel_hi:[1,1,1]
	v_pk_fma_f32 v[26:27], v[8:9], v[136:137], v[26:27] op_sel:[0,0,0] op_sel_hi:[0,1,1]
	v_pk_fma_f32 v[26:27], v[8:9], v[138:139], v[26:27] op_sel:[1,0,0] op_sel_hi:[1,1,1]
	ds_write2st64_b32 v50, v25, v27 offset0:120 offset1:124
	v_pk_mul_f32 v[10:11], v[10:11], v[140:141]
	v_pk_mul_f32 v[8:9], v[8:9], v[142:143]
	s_waitcnt lgkmcnt(7)
	v_pk_mul_f32 v[24:25], v[10:11], v[144:145]
	v_pk_fma_f32 v[24:25], v[8:9], v[146:147], v[24:25]
	v_add_f32_e32 v24, v24, v25
	s_waitcnt lgkmcnt(5)
	v_fma_f32 v16, v76, v156, v10
	v_fma_f32 v17, v77, v156, v11
	v_add_f32_dpp v15, v24, v24 row_ror:8 row_mask:0xf bank_mask:0xf bound_ctrl:1
	v_add_u32_e32 v51, 1, v51
	s_add_u32 s6, s6, 1
	v_add_f32_dpp v15, v15, v15 row_ror:4 row_mask:0xf bank_mask:0xf bound_ctrl:1
	ds_write_b32 v53, v51
	v_fma_f32 v18, v78, v156, v8
	v_add_f32_dpp v15, v15, v15 row_ror:2 row_mask:0xf bank_mask:0xf bound_ctrl:1
	v_fma_f32 v19, v79, v156, v9
	ds_read_b128 v[108:111], v34 offset:2048
	v_add_f32_dpp v30, v15, v15 row_ror:1 row_mask:0xf bank_mask:0xf bound_ctrl:1
	ds_read_b128 v[112:115], v34 offset:2304
	ds_read_b128 v[116:119], v34 offset:2560
	ds_read_b128 v[120:123], v34 offset:2816
	s_cmp_lt_u32 s6, 0x100
	s_cbranch_scc1 .Lsc_S_loop
	s_waitcnt lgkmcnt(0)
	s_branch .Lsc_item_end
	s_nop 0
	s_nop 0
	s_nop 0
	s_nop 0
	s_nop 0
	s_nop 0
	s_nop 0
	s_nop 0
	s_nop 0
	s_nop 0
	s_nop 0
	s_nop 0
	s_nop 0
	s_nop 0
	s_nop 0
	s_nop 0
	s_nop 0
